# stick-breaking loop: early-exit flags through ds ops (one b128 read) instead of four serialized flat loads, second P*V group's LDS reads batched; rowpass wave sums via DPP row scan + row totals instea
# speedup vs baseline: 1.0062x; 1.0062x over previous
.Lcvret_disp:
.Lhk_no:
	s_cmp_eq_u32 s19, 0
	s_cbranch_scc1 .Lp0_entry
	s_cmp_eq_u32 s19, 9
	s_cbranch_scc1 .Lgy_entry
	s_cmp_eq_u32 s19, 8
	s_cbranch_scc1 .Lup_entry
	s_cmp_eq_u32 s19, 6
	s_cbranch_scc1 .Lop_entry
	s_cmp_eq_u32 s19, 2
	s_cbranch_scc1 .Lpj_entry
	s_cmp_lt_i32 s19, 5
	s_cbranch_scc1 .LBB0_46
	s_and_b64 s[20:21], s[22:23], exec
	s_cselect_b32 s18, 0x18000, 0
	s_waitcnt lgkmcnt(0)
	s_add_u32 s66, s24, s18
	s_addc_u32 s80, s25, 0
	s_cmp_gt_i32 s19, 7
	s_cbranch_scc0 .LBB0_47
	s_cmp_gt_i32 s19, 8
	s_cbranch_scc0 .LBB0_48
	s_cmp_gt_i32 s19, 9
	s_cbranch_scc0 .LBB0_64
	s_mov_b64 s[20:21], 0
	s_mov_b64 s[24:25], 0
	s_cmp_eq_u32 s19, 10
	v_writelane_b32 v244, s20, 56
	s_nop 1
	v_writelane_b32 v244, s21, 57
	s_cbranch_scc0 .LBB0_65
	s_load_dwordx2 s[30:31], s[0:1], 0x68
	s_and_b64 vcc, exec, s[6:7]
	s_cbranch_vccz .LBB0_334
	s_lshl_b32 s18, s71, 2
	s_abs_i32 s6, s18
	v_cvt_f32_u32_e32 v0, s6
	s_waitcnt vmcnt(0)
	v_mov_b32_e32 v34, v154
	v_mov_b32_e32 v2, v154
	s_sub_i32 s26, 0, s6
	v_rcp_iflag_f32_e32 v0, v0
	s_nop 0
	v_mul_f32_e32 v0, 0x4f7ffffe, v0
	v_cvt_u32_f32_e32 v0, v0
	v_readfirstlane_b32 s7, v2
	s_ashr_i32 s20, s7, 6
	s_add_i32 s7, s18, 0x3fff
	v_readfirstlane_b32 s27, v0
	s_mul_i32 s26, s26, s27
	s_mul_hi_u32 s26, s27, s26
	s_xor_b32 s21, s7, s18
	s_abs_i32 s7, s7
	s_add_i32 s27, s27, s26
	s_mul_hi_u32 s26, s7, s27
	s_mul_i32 s27, s26, s6
	s_sub_i32 s7, s7, s27
	s_ashr_i32 s21, s21, 31
	s_add_i32 s27, s26, 1
	s_sub_i32 s28, s7, s6
	s_cmp_ge_u32 s7, s6
	s_cselect_b32 s26, s27, s26
	s_cselect_b32 s7, s28, s7
	s_add_i32 s27, s26, 1
	s_cmp_ge_u32 s7, s6
	s_cselect_b32 s6, s27, s26
	s_xor_b32 s6, s6, s21
	s_lshl_b32 s52, s3, 2
	s_sub_i32 s7, s6, s21
	s_add_i32 s6, s20, s52
	s_mul_i32 s6, s6, s7
	s_cmpk_gt_i32 s6, 0x3fff
	s_cbranch_scc1 .LBB0_335
	s_load_dwordx2 s[26:27], s[0:1], 0x110
	s_ashr_i32 s20, s6, 12
	s_mulk_i32 s20, 0x1800
	v_lshlrev_b32_e32 v0, 2, v34
	v_and_b32_e32 v35, 0xfc, v0
	s_waitcnt lgkmcnt(0)
	s_cmp_lg_u64 s[26:27], 0
	s_cselect_b64 s[40:41], -1, 0
	s_ashr_i32 s21, s20, 31
	s_lshl_b64 s[34:35], s[20:21], 2
	s_add_u32 s20, s66, s34
	s_addc_u32 s21, s80, s35
	s_add_u32 s36, s20, 0x5000
	s_addc_u32 s37, s21, 0
	s_and_b64 vcc, exec, s[40:41]
	v_lshlrev_b32_e32 v0, 2, v35
	s_cbranch_vccz .LBB0_30
	global_load_dwordx4 v[188:191], v0, s[36:37]
	s_add_u32 s54, s36, 0x30000
	s_addc_u32 s55, s37, 0
	global_load_dwordx4 v[192:195], v0, s[54:55]
	s_add_u32 s56, s36, 0x60000
	s_addc_u32 s57, s37, 0
	global_load_dwordx4 v[196:199], v0, s[56:57]
	s_add_u32 s62, s36, 0x90000
	s_addc_u32 s63, s37, 0
	global_load_dwordx4 v[200:203], v0, s[62:63]
	global_load_dwordx4 v[2:5], v0, s[30:31]
	s_waitcnt vmcnt(0)
	v_pk_add_f32 v[68:69], v[190:191], v[194:195]
	v_pk_add_f32 v[68:69], v[68:69], v[198:199]
	v_pk_add_f32 v[68:69], v[68:69], v[202:203]
	v_pk_add_f32 v[66:67], v[188:189], v[192:193]
	v_pk_add_f32 v[66:67], v[66:67], v[196:197]
	v_pk_add_f32 v[66:67], v[66:67], v[200:201]
.LBB0_30:
	s_load_dwordx2 s[20:21], s[0:1], 0xc0
	s_load_dwordx2 s[26:27], s[0:1], 0x20
	s_load_dwordx2 s[28:29], s[0:1], 0xb8
	s_waitcnt lgkmcnt(0)
	s_cmp_lg_u64 s[20:21], 0
	s_cselect_b64 s[50:51], -1, 0
	s_add_u32 s28, s28, s34
	s_addc_u32 s29, s29, s35
	s_add_u32 s42, s28, 0x19000
	s_addc_u32 s43, s29, 0
	s_add_u32 s34, s28, 0x18000
	s_addc_u32 s35, s29, 0
	s_add_u32 s48, s26, 0x1000
	s_addc_u32 s49, s27, 0
	s_cmp_eq_u64 s[20:21], 0
	s_cbranch_scc1 .LBB0_32
	global_load_dwordx4 v[188:191], v0, s[42:43]
	s_add_u32 s54, s42, 0x30000
	s_addc_u32 s55, s43, 0
	global_load_dwordx4 v[192:195], v0, s[54:55]
	s_mov_b32 s26, 0x60000
	global_load_dwordx4 v[6:9], v0, s[48:49]
	s_add_u32 s56, s42, 0x60000
	s_addc_u32 s57, s43, 0
	global_load_dwordx4 v[196:199], v0, s[56:57]
	s_add_u32 s62, s42, 0x90000
	s_addc_u32 s63, s43, 0
	global_load_dwordx4 v[200:203], v0, s[62:63]
	global_load_dwordx4 v[204:207], v0, s[34:35]
	s_add_u32 s54, s34, 0x30000
	s_addc_u32 s55, s35, 0
	global_load_dwordx4 v[208:211], v0, s[54:55]
	s_add_u32 s56, s34, 0x60000
	s_addc_u32 s57, s35, 0
	global_load_dwordx4 v[212:215], v0, s[56:57]
	s_mov_b32 s26, 0x90000
	s_add_u32 s62, s34, 0x90000
	s_addc_u32 s63, s35, 0
	global_load_dwordx4 v[216:219], v0, s[62:63]
	s_waitcnt vmcnt(0)
	v_pk_add_f32 v[72:73], v[190:191], v[194:195]
	v_pk_add_f32 v[72:73], v[72:73], v[198:199]
	v_pk_add_f32 v[72:73], v[72:73], v[202:203]
	v_pk_add_f32 v[72:73], v[72:73], 1.0 op_sel_hi:[1,0]
	v_pk_add_f32 v[70:71], v[188:189], v[192:193]
	v_pk_add_f32 v[70:71], v[70:71], v[196:197]
	v_pk_add_f32 v[70:71], v[70:71], v[200:201]
	v_pk_add_f32 v[70:71], v[70:71], 1.0 op_sel_hi:[1,0]
	v_pk_add_f32 v[76:77], v[206:207], v[210:211]
	v_pk_add_f32 v[76:77], v[76:77], v[214:215]
	v_pk_add_f32 v[76:77], v[76:77], v[218:219]
	v_pk_add_f32 v[74:75], v[204:205], v[208:209]
	v_pk_add_f32 v[74:75], v[74:75], v[212:213]
	v_pk_add_f32 v[74:75], v[74:75], v[216:217]
.LBB0_32:
	v_cndmask_b32_e64 v10, 0, 1, s[40:41]
	v_cmp_ne_u32_e64 s[38:39], 1, v10
	s_andn2_b64 vcc, exec, s[40:41]
	s_cbranch_vccnz .LBB0_34
	global_load_dwordx4 v[188:191], v0, s[36:37] offset:1024
	s_add_u32 s54, s36, 0x30000
	s_addc_u32 s55, s37, 0
	global_load_dwordx4 v[192:195], v0, s[54:55] offset:1024
	s_add_u32 s56, s36, 0x60000
	s_addc_u32 s57, s37, 0
	global_load_dwordx4 v[196:199], v0, s[56:57] offset:1024
	s_add_u32 s62, s36, 0x90000
	s_addc_u32 s63, s37, 0
	global_load_dwordx4 v[200:203], v0, s[62:63] offset:1024
	global_load_dwordx4 v[10:13], v0, s[30:31] offset:1024
	s_waitcnt vmcnt(0)
	v_pk_add_f32 v[80:81], v[190:191], v[194:195]
	v_pk_add_f32 v[80:81], v[80:81], v[198:199]
	v_pk_add_f32 v[80:81], v[80:81], v[202:203]
	v_pk_add_f32 v[78:79], v[188:189], v[192:193]
	v_pk_add_f32 v[78:79], v[78:79], v[196:197]
	v_pk_add_f32 v[78:79], v[78:79], v[200:201]
.LBB0_34:
	v_cndmask_b32_e64 v14, 0, 1, s[50:51]
	v_cmp_ne_u32_e64 s[40:41], 1, v14
	s_andn2_b64 vcc, exec, s[50:51]
	s_cbranch_vccnz .LBB0_36
	global_load_dwordx4 v[188:191], v0, s[42:43] offset:1024
	s_add_u32 s54, s42, 0x30000
	s_addc_u32 s55, s43, 0
	global_load_dwordx4 v[192:195], v0, s[54:55] offset:1024
	s_mov_b32 s26, 0x60000
	global_load_dwordx4 v[14:17], v0, s[48:49] offset:1024
	s_add_u32 s56, s42, 0x60000
	s_addc_u32 s57, s43, 0
	global_load_dwordx4 v[196:199], v0, s[56:57] offset:1024
	s_add_u32 s62, s42, 0x90000
	s_addc_u32 s63, s43, 0
	global_load_dwordx4 v[200:203], v0, s[62:63] offset:1024
	global_load_dwordx4 v[204:207], v0, s[34:35] offset:1024
	s_add_u32 s54, s34, 0x30000
	s_addc_u32 s55, s35, 0
	global_load_dwordx4 v[208:211], v0, s[54:55] offset:1024
	s_add_u32 s56, s34, 0x60000
	s_addc_u32 s57, s35, 0
	global_load_dwordx4 v[212:215], v0, s[56:57] offset:1024
	s_mov_b32 s26, 0x90000
	s_add_u32 s62, s34, 0x90000
	s_addc_u32 s63, s35, 0
	global_load_dwordx4 v[216:219], v0, s[62:63] offset:1024
	s_waitcnt vmcnt(0)
	v_pk_add_f32 v[84:85], v[190:191], v[194:195]
	v_pk_add_f32 v[84:85], v[84:85], v[198:199]
	v_pk_add_f32 v[84:85], v[84:85], v[202:203]
	v_pk_add_f32 v[84:85], v[84:85], 1.0 op_sel_hi:[1,0]
	v_pk_add_f32 v[82:83], v[188:189], v[192:193]
	v_pk_add_f32 v[82:83], v[82:83], v[196:197]
	v_pk_add_f32 v[82:83], v[82:83], v[200:201]
	v_pk_add_f32 v[82:83], v[82:83], 1.0 op_sel_hi:[1,0]
	v_pk_add_f32 v[88:89], v[206:207], v[210:211]
	v_pk_add_f32 v[88:89], v[88:89], v[214:215]
	v_pk_add_f32 v[88:89], v[88:89], v[218:219]
	v_pk_add_f32 v[86:87], v[204:205], v[208:209]
	v_pk_add_f32 v[86:87], v[86:87], v[212:213]
	v_pk_add_f32 v[86:87], v[86:87], v[216:217]
.LBB0_36:
	s_and_b64 vcc, exec, s[38:39]
	s_cbranch_vccnz .LBB0_38
	global_load_dwordx4 v[188:191], v0, s[36:37] offset:2048
	s_add_u32 s54, s36, 0x30000
	s_addc_u32 s55, s37, 0
	global_load_dwordx4 v[192:195], v0, s[54:55] offset:2048
	s_add_u32 s56, s36, 0x60000
	s_addc_u32 s57, s37, 0
	global_load_dwordx4 v[196:199], v0, s[56:57] offset:2048
	s_add_u32 s62, s36, 0x90000
	s_addc_u32 s63, s37, 0
	global_load_dwordx4 v[200:203], v0, s[62:63] offset:2048
	global_load_dwordx4 v[18:21], v0, s[30:31] offset:2048
	s_waitcnt vmcnt(0)
	v_pk_add_f32 v[92:93], v[190:191], v[194:195]
	v_pk_add_f32 v[92:93], v[92:93], v[198:199]
	v_pk_add_f32 v[92:93], v[92:93], v[202:203]
	v_pk_add_f32 v[90:91], v[188:189], v[192:193]
	v_pk_add_f32 v[90:91], v[90:91], v[196:197]
	v_pk_add_f32 v[90:91], v[90:91], v[200:201]
.LBB0_38:
	s_and_b64 vcc, exec, s[40:41]
	s_cbranch_vccnz .LBB0_40
	global_load_dwordx4 v[188:191], v0, s[42:43] offset:2048
	s_add_u32 s54, s42, 0x30000
	s_addc_u32 s55, s43, 0
	global_load_dwordx4 v[192:195], v0, s[54:55] offset:2048
	s_mov_b32 s26, 0x60000
	global_load_dwordx4 v[22:25], v0, s[48:49] offset:2048
	s_add_u32 s56, s42, 0x60000
	s_addc_u32 s57, s43, 0
	global_load_dwordx4 v[196:199], v0, s[56:57] offset:2048
	s_add_u32 s62, s42, 0x90000
	s_addc_u32 s63, s43, 0
	global_load_dwordx4 v[200:203], v0, s[62:63] offset:2048
	global_load_dwordx4 v[204:207], v0, s[34:35] offset:2048
	s_add_u32 s54, s34, 0x30000
	s_addc_u32 s55, s35, 0
	global_load_dwordx4 v[208:211], v0, s[54:55] offset:2048
	s_add_u32 s56, s34, 0x60000
	s_addc_u32 s57, s35, 0
	global_load_dwordx4 v[212:215], v0, s[56:57] offset:2048
	s_mov_b32 s26, 0x90000
	s_add_u32 s62, s34, 0x90000
	s_addc_u32 s63, s35, 0
	global_load_dwordx4 v[216:219], v0, s[62:63] offset:2048
	s_waitcnt vmcnt(0)
	v_pk_add_f32 v[96:97], v[190:191], v[194:195]
	v_pk_add_f32 v[96:97], v[96:97], v[198:199]
	v_pk_add_f32 v[96:97], v[96:97], v[202:203]
	v_pk_add_f32 v[96:97], v[96:97], 1.0 op_sel_hi:[1,0]
	v_pk_add_f32 v[94:95], v[188:189], v[192:193]
	v_pk_add_f32 v[94:95], v[94:95], v[196:197]
	v_pk_add_f32 v[94:95], v[94:95], v[200:201]
	v_pk_add_f32 v[94:95], v[94:95], 1.0 op_sel_hi:[1,0]
	v_pk_add_f32 v[108:109], v[206:207], v[210:211]
	v_pk_add_f32 v[108:109], v[108:109], v[214:215]
	v_pk_add_f32 v[108:109], v[108:109], v[218:219]
	v_pk_add_f32 v[106:107], v[204:205], v[208:209]
	v_pk_add_f32 v[106:107], v[106:107], v[212:213]
	v_pk_add_f32 v[106:107], v[106:107], v[216:217]
.LBB0_40:
	s_and_b64 vcc, exec, s[38:39]
	s_cbranch_vccnz .LBB0_42
	global_load_dwordx4 v[188:191], v0, s[36:37] offset:3072
	s_add_u32 s54, s36, 0x30000
	s_addc_u32 s55, s37, 0
	global_load_dwordx4 v[192:195], v0, s[54:55] offset:3072
	s_add_u32 s56, s36, 0x60000
	s_addc_u32 s57, s37, 0
	global_load_dwordx4 v[196:199], v0, s[56:57] offset:3072
	s_add_u32 s62, s36, 0x90000
	s_addc_u32 s63, s37, 0
	global_load_dwordx4 v[200:203], v0, s[62:63] offset:3072
	global_load_dwordx4 v[26:29], v0, s[30:31] offset:3072
	s_waitcnt vmcnt(0)
	v_pk_add_f32 v[112:113], v[190:191], v[194:195]
	v_pk_add_f32 v[112:113], v[112:113], v[198:199]
	v_pk_add_f32 v[112:113], v[112:113], v[202:203]
	v_pk_add_f32 v[110:111], v[188:189], v[192:193]
	v_pk_add_f32 v[110:111], v[110:111], v[196:197]
	v_pk_add_f32 v[110:111], v[110:111], v[200:201]
.LBB0_42:
	s_and_b64 vcc, exec, s[40:41]
	s_cbranch_vccnz .LBB0_44
	global_load_dwordx4 v[188:191], v0, s[42:43] offset:3072
	s_add_u32 s54, s42, 0x30000
	s_addc_u32 s55, s43, 0
	global_load_dwordx4 v[192:195], v0, s[54:55] offset:3072
	s_mov_b32 s26, 0x60000
	global_load_dwordx4 v[30:33], v0, s[48:49] offset:3072
	s_add_u32 s56, s42, 0x60000
	s_addc_u32 s57, s43, 0
	global_load_dwordx4 v[196:199], v0, s[56:57] offset:3072
	s_add_u32 s62, s42, 0x90000
	s_addc_u32 s63, s43, 0
	global_load_dwordx4 v[200:203], v0, s[62:63] offset:3072
	global_load_dwordx4 v[204:207], v0, s[34:35] offset:3072
	s_add_u32 s54, s34, 0x30000
	s_addc_u32 s55, s35, 0
	global_load_dwordx4 v[208:211], v0, s[54:55] offset:3072
	s_add_u32 s56, s34, 0x60000
	s_addc_u32 s57, s35, 0
	global_load_dwordx4 v[212:215], v0, s[56:57] offset:3072
	s_mov_b32 s26, 0x90000
	s_add_u32 s62, s34, 0x90000
	s_addc_u32 s63, s35, 0
	global_load_dwordx4 v[216:219], v0, s[62:63] offset:3072
	s_waitcnt vmcnt(0)
	v_pk_add_f32 v[116:117], v[190:191], v[194:195]
	v_pk_add_f32 v[116:117], v[116:117], v[198:199]
	v_pk_add_f32 v[116:117], v[116:117], v[202:203]
	v_pk_add_f32 v[116:117], v[116:117], 1.0 op_sel_hi:[1,0]
	v_pk_add_f32 v[114:115], v[188:189], v[192:193]
	v_pk_add_f32 v[114:115], v[114:115], v[196:197]
	v_pk_add_f32 v[114:115], v[114:115], v[200:201]
	v_pk_add_f32 v[114:115], v[114:115], 1.0 op_sel_hi:[1,0]
	v_pk_add_f32 v[120:121], v[206:207], v[210:211]
	v_pk_add_f32 v[120:121], v[120:121], v[214:215]
	v_pk_add_f32 v[120:121], v[120:121], v[218:219]
	v_pk_add_f32 v[118:119], v[204:205], v[208:209]
	v_pk_add_f32 v[118:119], v[118:119], v[212:213]
	v_pk_add_f32 v[118:119], v[118:119], v[216:217]

.LBB0_55:
	s_and_b64 vcc, exec, s[38:39]
	s_cbranch_vccnz .LBB0_57
	s_waitcnt vmcnt(3)
	v_and_b32_e32 v153, 0xffff0000, v148
	s_waitcnt vmcnt(2)
	v_and_b32_e32 v152, 0xffff0000, v146
	v_lshlrev_b32_e32 v151, 16, v148
	v_lshlrev_b32_e32 v150, 16, v146
	v_pk_mul_f32 v[172:173], v[152:153], v[152:153]
	s_waitcnt vmcnt(1)
	v_and_b32_e32 v177, 0xffff0000, v144
	s_waitcnt vmcnt(0)
	v_and_b32_e32 v176, 0xffff0000, v142
	v_lshlrev_b32_e32 v169, 16, v149
	v_lshlrev_b32_e32 v168, 16, v147
	v_pk_fma_f32 v[172:173], v[150:151], v[150:151], v[172:173]
	v_lshlrev_b32_e32 v175, 16, v144
	v_lshlrev_b32_e32 v174, 16, v142
	v_pk_mul_f32 v[182:183], v[176:177], v[176:177]
	v_and_b32_e32 v171, 0xffff0000, v149
	v_and_b32_e32 v170, 0xffff0000, v147
	v_pk_fma_f32 v[172:173], v[168:169], v[168:169], v[172:173]
	v_lshlrev_b32_e32 v179, 16, v145
	v_lshlrev_b32_e32 v178, 16, v143
	v_pk_fma_f32 v[182:183], v[174:175], v[174:175], v[182:183]
	v_pk_fma_f32 v[172:173], v[170:171], v[170:171], v[172:173]
	v_and_b32_e32 v181, 0xffff0000, v145
	v_and_b32_e32 v180, 0xffff0000, v143
	v_pk_fma_f32 v[182:183], v[178:179], v[178:179], v[182:183]
	v_pk_fma_f32 v[182:183], v[180:181], v[180:181], v[182:183]
	v_add_f32_e32 v0, v172, v173
	v_add_f32_e32 v0, v183, v0
	v_add_f32_e32 v0, v182, v0
	s_nop 1
	v_add_f32_dpp v0, v0, v0 row_shr:1 row_mask:0xf bank_mask:0xf
	s_nop 1
	v_add_f32_dpp v0, v0, v0 row_shr:2 row_mask:0xf bank_mask:0xf
	s_nop 1
	v_add_f32_dpp v0, v0, v0 row_shr:4 row_mask:0xf bank_mask:0xf
	s_nop 1
	v_add_f32_dpp v0, v0, v0 row_shr:8 row_mask:0xf bank_mask:0xf
	s_nop 1
	v_readlane_b32 s54, v0, 15
	v_readlane_b32 s55, v0, 31
	v_readlane_b32 s56, v0, 47
	v_readlane_b32 s57, v0, 63
	s_nop 3
	v_mov_b32_e32 v0, s54
	v_add_f32_e32 v0, s55, v0
	v_add_f32_e32 v0, s56, v0
	v_add_f32_e32 v0, s57, v0
	v_mov_b32_e32 v172, v169
	v_mov_b32_e32 v182, v151
	v_mov_b32_e32 v169, v170
	v_mov_b32_e32 v151, v152
	v_mov_b32_e32 v183, v153
	v_mov_b32_e32 v173, v171
	v_fmamk_f32 v0, v0, 0x3a800000, v155
	v_mul_f32_e32 v99, 0x4b800000, v0
	v_cmp_gt_f32_e32 vcc, s84, v0
	s_nop 1
	v_cndmask_b32_e32 v0, v0, v99, vcc
	v_rsq_f32_e32 v0, v0
	s_nop 0
	v_mul_f32_e32 v99, 0x45800000, v0
	v_cndmask_b32_e32 v0, v0, v99, vcc
	v_pk_mul_f32 v[168:169], v[168:169], v[0:1] op_sel_hi:[1,0]
	v_pk_mul_f32 v[150:151], v[150:151], v[0:1] op_sel_hi:[1,0]
	v_pk_mul_f32 v[152:153], v[80:81], v[168:169]
	v_pk_mul_f32 v[150:151], v[78:79], v[150:151]
	v_pk_fma_f32 v[60:61], v[12:13], v[152:153], v[60:61]
	v_pk_fma_f32 v[58:59], v[10:11], v[150:151], v[58:59]
	v_mov_b32_e32 v150, v179
	v_mov_b32_e32 v151, v181
	v_mov_b32_e32 v152, v175
	v_mov_b32_e32 v153, v177
	v_pk_mul_f32 v[150:151], v[150:151], v[0:1] op_sel_hi:[1,0]
	v_pk_mul_f32 v[152:153], v[152:153], v[0:1] op_sel_hi:[1,0]
	v_pk_mul_f32 v[150:151], v[92:93], v[150:151]
	v_pk_mul_f32 v[152:153], v[90:91], v[152:153]
	v_mov_b32_e32 v179, v180
	v_mov_b32_e32 v175, v176
	v_pk_mul_f32 v[172:173], v[172:173], v[0:1] op_sel_hi:[1,0]
	v_pk_mul_f32 v[182:183], v[182:183], v[0:1] op_sel_hi:[1,0]
	v_pk_fma_f32 v[56:57], v[20:21], v[150:151], v[56:57]
	v_pk_fma_f32 v[54:55], v[18:19], v[152:153], v[54:55]
	v_pk_mul_f32 v[150:151], v[178:179], v[0:1] op_sel_hi:[1,0]
	v_pk_mul_f32 v[152:153], v[174:175], v[0:1] op_sel_hi:[1,0]
	v_pk_mul_f32 v[182:183], v[66:67], v[182:183]
	v_pk_mul_f32 v[172:173], v[68:69], v[172:173]
	v_pk_mul_f32 v[152:153], v[110:111], v[152:153]
	v_pk_mul_f32 v[150:151], v[112:113], v[150:151]
	v_pk_fma_f32 v[64:65], v[4:5], v[172:173], v[64:65]
	v_pk_fma_f32 v[62:63], v[2:3], v[182:183], v[62:63]
	v_pk_fma_f32 v[52:53], v[28:29], v[150:151], v[52:53]
	v_pk_fma_f32 v[50:51], v[26:27], v[152:153], v[50:51]
	global_store_dwordx4 v[128:129], v[62:65], off offset:-2048 nt
	global_store_dwordx4 v[128:129], v[58:61], off offset:-1024 nt
	global_store_dwordx4 v[128:129], v[54:57], off nt
	global_store_dwordx4 v[128:129], v[50:53], off offset:1024 nt
.LBB0_57:
	s_and_b64 vcc, exec, s[40:41]
	s_cbranch_vccnz .LBB0_59
	s_nop 1
	v_mov_b32_e32 v152, v59
	v_mov_b32_e32 v153, v63
	v_mov_b32_e32 v150, v58
	v_mov_b32_e32 v151, v62
	v_pk_mul_f32 v[152:153], v[152:153], v[152:153]
	s_nop 1
	v_mov_b32_e32 v168, v51
	v_pk_fma_f32 v[150:151], v[150:151], v[150:151], v[152:153]
	v_mov_b32_e32 v152, v60
	v_mov_b32_e32 v153, v64
	v_pk_fma_f32 v[150:151], v[152:153], v[152:153], v[150:151]
	v_mov_b32_e32 v152, v61
	v_mov_b32_e32 v153, v65
	v_mov_b32_e32 v169, v55
	v_pk_fma_f32 v[150:151], v[152:153], v[152:153], v[150:151]
	v_mov_b32_e32 v152, v50
	v_mov_b32_e32 v153, v54
	v_pk_mul_f32 v[168:169], v[168:169], v[168:169]
	v_pk_fma_f32 v[152:153], v[152:153], v[152:153], v[168:169]
	v_mov_b32_e32 v168, v52
	v_mov_b32_e32 v169, v56
	v_pk_fma_f32 v[152:153], v[168:169], v[168:169], v[152:153]
	v_mov_b32_e32 v168, v53
	v_mov_b32_e32 v169, v57
	v_pk_fma_f32 v[152:153], v[168:169], v[168:169], v[152:153]
	v_add_f32_e32 v0, v150, v151
	v_add_f32_e32 v0, v153, v0
	v_add_f32_e32 v0, v152, v0
	s_nop 1
	v_add_f32_dpp v0, v0, v0 row_shr:1 row_mask:0xf bank_mask:0xf
	s_nop 1
	v_add_f32_dpp v0, v0, v0 row_shr:2 row_mask:0xf bank_mask:0xf
	s_nop 1
	v_add_f32_dpp v0, v0, v0 row_shr:4 row_mask:0xf bank_mask:0xf
	s_nop 1
	v_add_f32_dpp v0, v0, v0 row_shr:8 row_mask:0xf bank_mask:0xf
	s_nop 1
	v_readlane_b32 s54, v0, 15
	v_readlane_b32 s55, v0, 31
	v_readlane_b32 s56, v0, 47
	v_readlane_b32 s57, v0, 63
	s_nop 3
	v_mov_b32_e32 v0, s54
	v_add_f32_e32 v0, s55, v0
	v_add_f32_e32 v0, s56, v0
	v_add_f32_e32 v0, s57, v0
	v_fmamk_f32 v0, v0, 0x3a800000, v155
	v_mul_f32_e32 v99, 0x4b800000, v0
	v_cmp_gt_f32_e32 vcc, s84, v0
	s_nop 1
	v_cndmask_b32_e32 v0, v0, v99, vcc
	v_rsq_f32_e32 v0, v0
	s_nop 0
	v_mul_f32_e32 v99, 0x45800000, v0
	v_cndmask_b32_e32 v0, v0, v99, vcc
	v_pk_mul_f32 v[64:65], v[64:65], v[0:1] op_sel_hi:[1,0]
	v_pk_mul_f32 v[62:63], v[62:63], v[0:1] op_sel_hi:[1,0]
	v_pk_mul_f32 v[60:61], v[60:61], v[0:1] op_sel_hi:[1,0]
	v_pk_mul_f32 v[58:59], v[58:59], v[0:1] op_sel_hi:[1,0]
	v_pk_mul_f32 v[56:57], v[56:57], v[0:1] op_sel_hi:[1,0]
	v_pk_mul_f32 v[54:55], v[54:55], v[0:1] op_sel_hi:[1,0]
	v_pk_mul_f32 v[52:53], v[52:53], v[0:1] op_sel_hi:[1,0]
	v_pk_mul_f32 v[50:51], v[50:51], v[0:1] op_sel_hi:[1,0]
	v_pk_mul_f32 v[62:63], v[6:7], v[62:63]
	v_pk_mul_f32 v[64:65], v[8:9], v[64:65]
	v_pk_mul_f32 v[58:59], v[14:15], v[58:59]
	v_pk_mul_f32 v[60:61], v[16:17], v[60:61]
	v_pk_mul_f32 v[54:55], v[22:23], v[54:55]
	v_pk_mul_f32 v[56:57], v[24:25], v[56:57]
	v_pk_mul_f32 v[50:51], v[30:31], v[50:51]
	v_pk_mul_f32 v[52:53], v[32:33], v[52:53]
	v_pk_fma_f32 v[64:65], v[72:73], v[64:65], v[76:77]
	v_pk_fma_f32 v[62:63], v[70:71], v[62:63], v[74:75]
	v_pk_fma_f32 v[60:61], v[84:85], v[60:61], v[88:89]
	v_pk_fma_f32 v[58:59], v[82:83], v[58:59], v[86:87]
	v_pk_fma_f32 v[56:57], v[96:97], v[56:57], v[108:109]
	v_pk_fma_f32 v[54:55], v[94:95], v[54:55], v[106:107]
	v_pk_fma_f32 v[52:53], v[116:117], v[52:53], v[120:121]
	v_pk_fma_f32 v[50:51], v[114:115], v[50:51], v[118:119]
	v_cvt_pk_bf16_f32 v62, v62, v63
	v_cvt_pk_bf16_f32 v63, v64, v65
	v_cvt_pk_bf16_f32 v58, v58, v59
	v_cvt_pk_bf16_f32 v59, v60, v61
	v_cvt_pk_bf16_f32 v54, v54, v55
	v_cvt_pk_bf16_f32 v55, v56, v57
	v_cvt_pk_bf16_f32 v50, v50, v51
	v_cvt_pk_bf16_f32 v51, v52, v53
	v_readlane_b32 vcc_lo, v244, 60
	v_readlane_b32 vcc_hi, v244, 61
	s_nop 3
	v_subrev_u32_e32 v64, vcc_lo, v132
	v_add_u32_e32 v64, 0xfffffc00, v64
	v_and_b32_e32 v60, 0x7ff, v64
	v_lshrrev_b32_e32 v64, 11, v64
	v_lshlrev_b32_e32 v64, 6, v64
	v_lshrrev_b32_e32 v61, 6, v60
	v_lshl_or_b32 v64, v61, 20, v64
	v_and_or_b32 v64, v60, 63, v64
	v_mov_b32_e32 v65, 0
	v_lshl_add_u64 v[64:65], vcc, 0, v[64:65]
	global_store_dwordx2 v[64:65], v[62:63], off
	v_subrev_u32_e32 v64, vcc_lo, v132
	v_add_u32_e32 v64, 0xfffffe00, v64
	v_and_b32_e32 v60, 0x7ff, v64
	v_lshrrev_b32_e32 v64, 11, v64
	v_lshlrev_b32_e32 v64, 6, v64
	v_lshrrev_b32_e32 v61, 6, v60
	v_lshl_or_b32 v64, v61, 20, v64
	v_and_or_b32 v64, v60, 63, v64
	v_mov_b32_e32 v65, 0
	v_lshl_add_u64 v[64:65], vcc, 0, v[64:65]
	global_store_dwordx2 v[64:65], v[58:59], off
	v_subrev_u32_e32 v64, vcc_lo, v132
	v_and_b32_e32 v60, 0x7ff, v64
	v_lshrrev_b32_e32 v64, 11, v64
	v_lshlrev_b32_e32 v64, 6, v64
	v_lshrrev_b32_e32 v61, 6, v60
	v_lshl_or_b32 v64, v61, 20, v64
	v_and_or_b32 v64, v60, 63, v64
	v_mov_b32_e32 v65, 0
	v_lshl_add_u64 v[64:65], vcc, 0, v[64:65]
	global_store_dwordx2 v[64:65], v[54:55], off
	v_subrev_u32_e32 v64, vcc_lo, v132
	v_add_u32_e32 v64, 0x200, v64
	v_and_b32_e32 v60, 0x7ff, v64
	v_lshrrev_b32_e32 v64, 11, v64
	v_lshlrev_b32_e32 v64, 6, v64
	v_lshrrev_b32_e32 v61, 6, v60
	v_lshl_or_b32 v64, v61, 20, v64
	v_and_or_b32 v64, v60, 63, v64
	v_mov_b32_e32 v65, 0
	v_lshl_add_u64 v[64:65], vcc, 0, v[64:65]
	global_store_dwordx2 v[64:65], v[50:51], off
.LBB0_59:
	s_andn2_b64 vcc, exec, s[34:35]
	s_cbranch_vccnz .LBB0_49
	s_and_b64 vcc, exec, s[38:39]
	s_cbranch_vccnz .LBB0_62
	s_nop 1
	v_and_b32_e32 v53, 0xffff0000, v140
	v_and_b32_e32 v52, 0xffff0000, v138
	v_lshlrev_b32_e32 v51, 16, v140
	v_lshlrev_b32_e32 v50, 16, v138
	v_pk_mul_f32 v[58:59], v[52:53], v[52:53]
	v_lshlrev_b32_e32 v55, 16, v141
	v_lshlrev_b32_e32 v54, 16, v139
	v_pk_fma_f32 v[58:59], v[50:51], v[50:51], v[58:59]
	v_and_b32_e32 v57, 0xffff0000, v141
	v_and_b32_e32 v56, 0xffff0000, v139
	v_pk_fma_f32 v[58:59], v[54:55], v[54:55], v[58:59]
	v_and_b32_e32 v63, 0xffff0000, v136
	v_and_b32_e32 v62, 0xffff0000, v134
	v_pk_fma_f32 v[58:59], v[56:57], v[56:57], v[58:59]
	v_lshlrev_b32_e32 v61, 16, v136
	v_lshlrev_b32_e32 v60, 16, v134
	v_pk_mul_f32 v[152:153], v[62:63], v[62:63]
	v_lshlrev_b32_e32 v65, 16, v137
	v_lshlrev_b32_e32 v64, 16, v135
	v_pk_fma_f32 v[152:153], v[60:61], v[60:61], v[152:153]
	v_add_f32_e32 v0, v58, v59
	v_and_b32_e32 v151, 0xffff0000, v137
	v_and_b32_e32 v150, 0xffff0000, v135
	v_pk_fma_f32 v[152:153], v[64:65], v[64:65], v[152:153]
	v_pk_fma_f32 v[152:153], v[150:151], v[150:151], v[152:153]
	v_add_f32_e32 v0, v153, v0
	v_add_f32_e32 v0, v152, v0
	s_nop 1
	v_add_f32_dpp v0, v0, v0 row_shr:1 row_mask:0xf bank_mask:0xf
	s_nop 1
	v_add_f32_dpp v0, v0, v0 row_shr:2 row_mask:0xf bank_mask:0xf
	s_nop 1
	v_add_f32_dpp v0, v0, v0 row_shr:4 row_mask:0xf bank_mask:0xf
	s_nop 1
	v_add_f32_dpp v0, v0, v0 row_shr:8 row_mask:0xf bank_mask:0xf
	s_nop 1
	v_readlane_b32 s54, v0, 15
	v_readlane_b32 s55, v0, 31
	v_readlane_b32 s56, v0, 47
	v_readlane_b32 s57, v0, 63
	s_nop 3
	v_mov_b32_e32 v0, s54
	v_add_f32_e32 v0, s55, v0
	v_add_f32_e32 v0, s56, v0
	v_add_f32_e32 v0, s57, v0
	v_mov_b32_e32 v152, v55
	v_mov_b32_e32 v168, v51
	v_mov_b32_e32 v55, v56
	v_mov_b32_e32 v51, v52
	v_mov_b32_e32 v169, v53
	v_mov_b32_e32 v153, v57
	s_ashr_i32 s21, s20, 31
	s_lshl_b64 s[26:27], s[20:21], 12
	v_fmamk_f32 v0, v0, 0x3a800000, v155
	v_mul_f32_e32 v58, 0x4b800000, v0
	v_cmp_gt_f32_e32 vcc, s84, v0
	s_nop 1
	v_cndmask_b32_e32 v0, v0, v58, vcc
	v_rsq_f32_e32 v0, v0
	s_nop 0
	v_mul_f32_e32 v58, 0x45800000, v0
	v_cndmask_b32_e32 v0, v0, v58, vcc
	v_pk_mul_f32 v[54:55], v[54:55], v[0:1] op_sel_hi:[1,0]
	v_pk_mul_f32 v[50:51], v[50:51], v[0:1] op_sel_hi:[1,0]
	v_pk_mul_f32 v[52:53], v[80:81], v[54:55]
	v_pk_mul_f32 v[50:51], v[78:79], v[50:51]
	v_pk_fma_f32 v[40:41], v[12:13], v[52:53], v[40:41]
	v_pk_fma_f32 v[38:39], v[10:11], v[50:51], v[38:39]
	v_mov_b32_e32 v50, v65
	v_mov_b32_e32 v51, v151
	v_mov_b32_e32 v52, v61
	v_mov_b32_e32 v53, v63
	v_pk_mul_f32 v[50:51], v[50:51], v[0:1] op_sel_hi:[1,0]
	v_pk_mul_f32 v[52:53], v[52:53], v[0:1] op_sel_hi:[1,0]
	v_pk_mul_f32 v[50:51], v[92:93], v[50:51]
	v_pk_mul_f32 v[52:53], v[90:91], v[52:53]
	v_mov_b32_e32 v65, v150
	v_mov_b32_e32 v61, v62
	v_pk_mul_f32 v[152:153], v[152:153], v[0:1] op_sel_hi:[1,0]
	v_pk_mul_f32 v[168:169], v[168:169], v[0:1] op_sel_hi:[1,0]
	v_pk_fma_f32 v[44:45], v[20:21], v[50:51], v[44:45]
	v_pk_fma_f32 v[42:43], v[18:19], v[52:53], v[42:43]
	v_pk_mul_f32 v[50:51], v[64:65], v[0:1] op_sel_hi:[1,0]
	v_pk_mul_f32 v[52:53], v[60:61], v[0:1] op_sel_hi:[1,0]
	v_pk_mul_f32 v[168:169], v[66:67], v[168:169]
	v_pk_mul_f32 v[152:153], v[68:69], v[152:153]
	v_pk_mul_f32 v[52:53], v[110:111], v[52:53]
	v_pk_mul_f32 v[50:51], v[112:113], v[50:51]
	v_lshl_add_u64 v[58:59], v[122:123], 0, s[26:27]
	v_pk_fma_f32 v[36:37], v[4:5], v[152:153], v[36:37]
	v_pk_fma_f32 v[34:35], v[2:3], v[168:169], v[34:35]
	v_pk_fma_f32 v[48:49], v[28:29], v[50:51], v[48:49]
	v_pk_fma_f32 v[46:47], v[26:27], v[52:53], v[46:47]
	global_store_dwordx4 v[58:59], v[34:37], off nt
	global_store_dwordx4 v[58:59], v[38:41], off offset:1024 nt
	global_store_dwordx4 v[58:59], v[42:45], off offset:2048 nt
	global_store_dwordx4 v[58:59], v[46:49], off offset:3072 nt
.LBB0_62:
	s_and_b64 vcc, exec, s[40:41]
	s_cbranch_vccnz .LBB0_49
	s_nop 1
	v_mov_b32_e32 v52, v39
	v_mov_b32_e32 v53, v35
	v_mov_b32_e32 v50, v38
	v_mov_b32_e32 v51, v34
	v_pk_mul_f32 v[52:53], v[52:53], v[52:53]
	v_mov_b32_e32 v54, v47
	v_pk_fma_f32 v[50:51], v[50:51], v[50:51], v[52:53]
	v_mov_b32_e32 v52, v40
	v_mov_b32_e32 v53, v36
	v_pk_fma_f32 v[50:51], v[52:53], v[52:53], v[50:51]
	v_mov_b32_e32 v52, v41
	v_mov_b32_e32 v53, v37
	v_mov_b32_e32 v55, v43
	v_pk_fma_f32 v[50:51], v[52:53], v[52:53], v[50:51]
	v_mov_b32_e32 v52, v46
	v_mov_b32_e32 v53, v42
	v_pk_mul_f32 v[54:55], v[54:55], v[54:55]
	v_add_f32_e32 v0, v50, v51
	v_pk_fma_f32 v[52:53], v[52:53], v[52:53], v[54:55]
	v_mov_b32_e32 v54, v48
	v_mov_b32_e32 v55, v44
	v_pk_fma_f32 v[52:53], v[54:55], v[54:55], v[52:53]
	v_mov_b32_e32 v54, v49
	v_mov_b32_e32 v55, v45
	v_pk_fma_f32 v[52:53], v[54:55], v[54:55], v[52:53]
	v_add_f32_e32 v0, v53, v0
	v_add_f32_e32 v0, v52, v0
	s_nop 1
	v_add_f32_dpp v0, v0, v0 row_shr:1 row_mask:0xf bank_mask:0xf
	s_nop 1
	v_add_f32_dpp v0, v0, v0 row_shr:2 row_mask:0xf bank_mask:0xf
	s_nop 1
	v_add_f32_dpp v0, v0, v0 row_shr:4 row_mask:0xf bank_mask:0xf
	s_nop 1
	v_add_f32_dpp v0, v0, v0 row_shr:8 row_mask:0xf bank_mask:0xf
	s_nop 1
	v_readlane_b32 s54, v0, 15
	v_readlane_b32 s55, v0, 31
	v_readlane_b32 s56, v0, 47
	v_readlane_b32 s57, v0, 63
	s_nop 3
	v_mov_b32_e32 v0, s54
	v_add_f32_e32 v0, s55, v0
	v_add_f32_e32 v0, s56, v0
	v_add_f32_e32 v0, s57, v0
	s_ashr_i32 s21, s20, 31
	s_lshl_b64 s[20:21], s[20:21], 11
	v_fmamk_f32 v0, v0, 0x3a800000, v155
	v_mul_f32_e32 v50, 0x4b800000, v0
	v_cmp_gt_f32_e32 vcc, s84, v0
	s_nop 1
	v_cndmask_b32_e32 v0, v0, v50, vcc
	v_rsq_f32_e32 v0, v0
	s_nop 0
	v_mul_f32_e32 v50, 0x45800000, v0
	v_cndmask_b32_e32 v0, v0, v50, vcc
	v_pk_mul_f32 v[52:53], v[36:37], v[0:1] op_sel_hi:[1,0]
	v_pk_mul_f32 v[54:55], v[34:35], v[0:1] op_sel_hi:[1,0]
	v_pk_mul_f32 v[52:53], v[8:9], v[52:53]
	v_pk_mul_f32 v[54:55], v[6:7], v[54:55]
	v_pk_fma_f32 v[52:53], v[72:73], v[52:53], v[76:77]
	v_pk_fma_f32 v[54:55], v[70:71], v[54:55], v[74:75]
	v_lshl_add_u64 v[50:51], v[126:127], 0, s[20:21]
	v_cvt_pk_bf16_f32 v54, v54, v55
	v_cvt_pk_bf16_f32 v55, v52, v53
	v_readlane_b32 vcc_lo, v244, 60
	v_readlane_b32 vcc_hi, v244, 61
	s_nop 3
	v_subrev_u32_e32 v34, vcc_lo, v50
	v_and_b32_e32 v36, 0x7ff, v34
	v_lshrrev_b32_e32 v34, 11, v34
	v_lshlrev_b32_e32 v34, 6, v34
	v_lshrrev_b32_e32 v37, 6, v36
	v_lshl_or_b32 v34, v37, 20, v34
	v_and_or_b32 v34, v36, 63, v34
	v_mov_b32_e32 v35, 0
	v_lshl_add_u64 v[34:35], vcc, 0, v[34:35]
	global_store_dwordx2 v[34:35], v[54:55], off
	v_pk_mul_f32 v[52:53], v[40:41], v[0:1] op_sel_hi:[1,0]
	v_pk_mul_f32 v[54:55], v[38:39], v[0:1] op_sel_hi:[1,0]
	v_pk_mul_f32 v[52:53], v[16:17], v[52:53]
	v_pk_mul_f32 v[54:55], v[14:15], v[54:55]
	v_pk_fma_f32 v[52:53], v[84:85], v[52:53], v[88:89]
	v_pk_fma_f32 v[54:55], v[82:83], v[54:55], v[86:87]
	s_nop 0
	v_cvt_pk_bf16_f32 v54, v54, v55
	v_cvt_pk_bf16_f32 v55, v52, v53
	v_subrev_u32_e32 v34, vcc_lo, v50
	v_add_u32_e32 v34, 0x200, v34
	v_and_b32_e32 v36, 0x7ff, v34
	v_lshrrev_b32_e32 v34, 11, v34
	v_lshlrev_b32_e32 v34, 6, v34
	v_lshrrev_b32_e32 v37, 6, v36
	v_lshl_or_b32 v34, v37, 20, v34
	v_and_or_b32 v34, v36, 63, v34
	v_mov_b32_e32 v35, 0
	v_lshl_add_u64 v[34:35], vcc, 0, v[34:35]
	global_store_dwordx2 v[34:35], v[54:55], off
	v_pk_mul_f32 v[52:53], v[44:45], v[0:1] op_sel_hi:[1,0]
	v_pk_mul_f32 v[54:55], v[42:43], v[0:1] op_sel_hi:[1,0]
	v_pk_mul_f32 v[52:53], v[24:25], v[52:53]
	v_pk_mul_f32 v[54:55], v[22:23], v[54:55]
	v_pk_fma_f32 v[52:53], v[96:97], v[52:53], v[108:109]
	v_pk_fma_f32 v[54:55], v[94:95], v[54:55], v[106:107]
	s_nop 0
	v_cvt_pk_bf16_f32 v54, v54, v55
	v_cvt_pk_bf16_f32 v55, v52, v53
	v_subrev_u32_e32 v34, vcc_lo, v50
	v_add_u32_e32 v34, 0x400, v34
	v_and_b32_e32 v36, 0x7ff, v34
	v_lshrrev_b32_e32 v34, 11, v34
	v_lshlrev_b32_e32 v34, 6, v34
	v_lshrrev_b32_e32 v37, 6, v36
	v_lshl_or_b32 v34, v37, 20, v34
	v_and_or_b32 v34, v36, 63, v34
	v_mov_b32_e32 v35, 0
	v_lshl_add_u64 v[34:35], vcc, 0, v[34:35]
	global_store_dwordx2 v[34:35], v[54:55], off
	v_pk_mul_f32 v[52:53], v[48:49], v[0:1] op_sel_hi:[1,0]
	v_pk_mul_f32 v[54:55], v[46:47], v[0:1] op_sel_hi:[1,0]
	v_pk_mul_f32 v[52:53], v[32:33], v[52:53]
	v_pk_mul_f32 v[54:55], v[30:31], v[54:55]
	v_pk_fma_f32 v[52:53], v[116:117], v[52:53], v[120:121]
	v_pk_fma_f32 v[54:55], v[114:115], v[54:55], v[118:119]
	s_nop 0
	v_cvt_pk_bf16_f32 v54, v54, v55
	v_cvt_pk_bf16_f32 v55, v52, v53
	v_subrev_u32_e32 v34, vcc_lo, v50
	v_add_u32_e32 v34, 0x600, v34
	v_and_b32_e32 v36, 0x7ff, v34
	v_lshrrev_b32_e32 v34, 11, v34
	v_lshlrev_b32_e32 v34, 6, v34
	v_lshrrev_b32_e32 v37, 6, v36
	v_lshl_or_b32 v34, v37, 20, v34
	v_and_or_b32 v34, v36, 63, v34
	v_mov_b32_e32 v35, 0
	v_lshl_add_u64 v[34:35], vcc, 0, v[34:35]
	global_store_dwordx2 v[34:35], v[54:55], off
	s_branch .LBB0_49

.LBB0_121:
	s_cmp_lt_i32 s19, 6
	s_mov_b64 s[6:7], -1
	s_cbranch_scc1 .LBB0_175
	s_cmp_gt_i32 s19, 6
	s_cbranch_scc0 .LBB0_158
	s_lshl_b32 s6, s71, 2
	s_abs_i32 s7, s6
	v_cvt_f32_u32_e32 v0, s7
	s_sub_i32 s21, 0, s7
	s_add_i32 s20, s6, 0x3fff
	s_xor_b32 s6, s20, s6
	v_rcp_iflag_f32_e32 v0, v0
	s_abs_i32 s20, s20
	s_waitcnt vmcnt(0)
	v_mov_b32_e32 v34, v154
	v_mov_b32_e32 v2, v154
	v_mul_f32_e32 v0, 0x4f7ffffe, v0
	v_cvt_u32_f32_e32 v0, v0
	s_ashr_i32 s6, s6, 31
	v_readfirstlane_b32 s24, v0
	s_mul_i32 s21, s21, s24
	s_mul_hi_u32 s21, s24, s21
	s_add_i32 s24, s24, s21
	s_mul_hi_u32 s21, s20, s24
	s_mul_i32 s24, s21, s7
	v_readfirstlane_b32 s18, v2
	s_sub_i32 s20, s20, s24
	s_ashr_i32 s18, s18, 6
	s_add_i32 s24, s21, 1
	s_sub_i32 s25, s20, s7
	s_cmp_ge_u32 s20, s7
	s_cselect_b32 s21, s24, s21
	s_cselect_b32 s20, s25, s20
	s_add_i32 s24, s21, 1
	s_cmp_ge_u32 s20, s7
	s_cselect_b32 s7, s24, s21
	s_xor_b32 s7, s7, s6
	s_sub_i32 s7, s7, s6
	s_lshl_b32 s6, s3, 2
	s_add_i32 s6, s18, s6
	s_mul_i32 s6, s6, s7
	s_cmpk_gt_i32 s6, 0x3fff
	s_cbranch_scc1 .LBB0_157
	s_load_dwordx2 s[20:21], s[0:1], 0x28
	s_load_dwordx2 s[24:25], s[0:1], 0x110
	s_and_b64 s[26:27], s[22:23], exec
	s_cselect_b32 s18, 0x400, 0
	s_lshl_b32 s18, s18, 2
	s_waitcnt lgkmcnt(0)
	s_add_u32 s28, s20, s18
	s_addc_u32 s29, s21, 0
	s_ashr_i32 s20, s6, 12
	s_cmp_lg_u64 s[24:25], 0
	s_mulk_i32 s20, 0x1800
	s_cselect_b64 s[40:41], -1, 0
	s_ashr_i32 s21, s20, 31
	s_lshl_b64 s[30:31], s[20:21], 2
	s_add_u32 s20, s66, s30
	v_lshlrev_b32_e32 v0, 2, v34
	s_addc_u32 s21, s80, s31
	v_and_b32_e32 v35, 0xfc, v0
	s_add_u32 s34, s20, 0x2000
	s_addc_u32 s35, s21, 0
	s_and_b64 vcc, exec, s[40:41]
	v_lshlrev_b32_e32 v0, 2, v35
	s_cbranch_vccz .LBB0_126
	global_load_dwordx4 v[188:191], v0, s[34:35]
	s_add_u32 s54, s34, 0x30000
	s_addc_u32 s55, s35, 0
	global_load_dwordx4 v[192:195], v0, s[54:55]
	s_add_u32 s56, s34, 0x60000
	s_addc_u32 s57, s35, 0
	global_load_dwordx4 v[196:199], v0, s[56:57]
	s_add_u32 s62, s34, 0x90000
	s_addc_u32 s63, s35, 0
	global_load_dwordx4 v[200:203], v0, s[62:63]
	global_load_dwordx4 v[2:5], v0, s[28:29]
	s_waitcnt vmcnt(0)
	v_pk_add_f32 v[68:69], v[190:191], v[194:195]
	v_pk_add_f32 v[68:69], v[68:69], v[198:199]
	v_pk_add_f32 v[68:69], v[68:69], v[202:203]
	v_pk_add_f32 v[66:67], v[188:189], v[192:193]
	v_pk_add_f32 v[66:67], v[66:67], v[196:197]
	v_pk_add_f32 v[66:67], v[66:67], v[200:201]
.LBB0_126:
	s_load_dwordx2 s[26:27], s[0:1], 0xc0
	s_load_dwordx2 s[20:21], s[0:1], 0x60
	s_waitcnt lgkmcnt(0)
	s_cmp_lg_u64 s[26:27], 0
	s_cselect_b64 s[48:49], -1, 0
	s_add_u32 s30, s66, s30
	s_addc_u32 s31, s80, s31
	s_add_u32 s36, s30, 0x4000
	s_addc_u32 s37, s31, 0
	s_add_u32 s30, s30, 0x3000
	s_addc_u32 s31, s31, 0
	s_add_u32 s42, s20, s18
	s_addc_u32 s43, s21, 0
	s_cmp_eq_u64 s[26:27], 0
	s_cbranch_scc1 .LBB0_128
	global_load_dwordx4 v[188:191], v0, s[36:37]
	s_add_u32 s54, s36, 0x30000
	s_addc_u32 s55, s37, 0
	global_load_dwordx4 v[192:195], v0, s[54:55]
	s_mov_b32 s18, 0x60000
	global_load_dwordx4 v[6:9], v0, s[42:43]
	s_add_u32 s56, s36, 0x60000
	s_addc_u32 s57, s37, 0
	global_load_dwordx4 v[196:199], v0, s[56:57]
	s_add_u32 s62, s36, 0x90000
	s_addc_u32 s63, s37, 0
	global_load_dwordx4 v[200:203], v0, s[62:63]
	global_load_dwordx4 v[204:207], v0, s[30:31]
	s_add_u32 s54, s30, 0x30000
	s_addc_u32 s55, s31, 0
	global_load_dwordx4 v[208:211], v0, s[54:55]
	s_add_u32 s56, s30, 0x60000
	s_addc_u32 s57, s31, 0
	global_load_dwordx4 v[212:215], v0, s[56:57]
	s_mov_b32 s18, 0x90000
	s_add_u32 s62, s30, 0x90000
	s_addc_u32 s63, s31, 0
	global_load_dwordx4 v[216:219], v0, s[62:63]
	s_waitcnt vmcnt(0)
	v_pk_add_f32 v[72:73], v[190:191], v[194:195]
	v_pk_add_f32 v[72:73], v[72:73], v[198:199]
	v_pk_add_f32 v[72:73], v[72:73], v[202:203]
	v_pk_add_f32 v[72:73], v[72:73], 1.0 op_sel_hi:[1,0]
	v_pk_add_f32 v[70:71], v[188:189], v[192:193]
	v_pk_add_f32 v[70:71], v[70:71], v[196:197]
	v_pk_add_f32 v[70:71], v[70:71], v[200:201]
	v_pk_add_f32 v[70:71], v[70:71], 1.0 op_sel_hi:[1,0]
	v_pk_add_f32 v[76:77], v[206:207], v[210:211]
	v_pk_add_f32 v[76:77], v[76:77], v[214:215]
	v_pk_add_f32 v[76:77], v[76:77], v[218:219]
	v_pk_add_f32 v[74:75], v[204:205], v[208:209]
	v_pk_add_f32 v[74:75], v[74:75], v[212:213]
	v_pk_add_f32 v[74:75], v[74:75], v[216:217]
.LBB0_128:
	v_cndmask_b32_e64 v10, 0, 1, s[40:41]
	v_cmp_ne_u32_e64 s[38:39], 1, v10
	s_andn2_b64 vcc, exec, s[40:41]
	s_cbranch_vccnz .LBB0_130
	global_load_dwordx4 v[188:191], v0, s[34:35] offset:1024
	s_add_u32 s54, s34, 0x30000
	s_addc_u32 s55, s35, 0
	global_load_dwordx4 v[192:195], v0, s[54:55] offset:1024
	s_add_u32 s56, s34, 0x60000
	s_addc_u32 s57, s35, 0
	global_load_dwordx4 v[196:199], v0, s[56:57] offset:1024
	s_add_u32 s62, s34, 0x90000
	s_addc_u32 s63, s35, 0
	global_load_dwordx4 v[200:203], v0, s[62:63] offset:1024
	global_load_dwordx4 v[10:13], v0, s[28:29] offset:1024
	s_waitcnt vmcnt(0)
	v_pk_add_f32 v[80:81], v[190:191], v[194:195]
	v_pk_add_f32 v[80:81], v[80:81], v[198:199]
	v_pk_add_f32 v[80:81], v[80:81], v[202:203]
	v_pk_add_f32 v[78:79], v[188:189], v[192:193]
	v_pk_add_f32 v[78:79], v[78:79], v[196:197]
	v_pk_add_f32 v[78:79], v[78:79], v[200:201]
.LBB0_130:
	v_cndmask_b32_e64 v14, 0, 1, s[48:49]
	v_cmp_ne_u32_e64 s[40:41], 1, v14
	s_andn2_b64 vcc, exec, s[48:49]
	s_cbranch_vccnz .LBB0_132
	global_load_dwordx4 v[188:191], v0, s[36:37] offset:1024
	s_add_u32 s54, s36, 0x30000
	s_addc_u32 s55, s37, 0
	global_load_dwordx4 v[192:195], v0, s[54:55] offset:1024
	s_mov_b32 s18, 0x60000
	global_load_dwordx4 v[14:17], v0, s[42:43] offset:1024
	s_add_u32 s56, s36, 0x60000
	s_addc_u32 s57, s37, 0
	global_load_dwordx4 v[196:199], v0, s[56:57] offset:1024
	s_add_u32 s62, s36, 0x90000
	s_addc_u32 s63, s37, 0
	global_load_dwordx4 v[200:203], v0, s[62:63] offset:1024
	global_load_dwordx4 v[204:207], v0, s[30:31] offset:1024
	s_add_u32 s54, s30, 0x30000
	s_addc_u32 s55, s31, 0
	global_load_dwordx4 v[208:211], v0, s[54:55] offset:1024
	s_add_u32 s56, s30, 0x60000
	s_addc_u32 s57, s31, 0
	global_load_dwordx4 v[212:215], v0, s[56:57] offset:1024
	s_mov_b32 s18, 0x90000
	s_add_u32 s62, s30, 0x90000
	s_addc_u32 s63, s31, 0
	global_load_dwordx4 v[216:219], v0, s[62:63] offset:1024
	s_waitcnt vmcnt(0)
	v_pk_add_f32 v[84:85], v[190:191], v[194:195]
	v_pk_add_f32 v[84:85], v[84:85], v[198:199]
	v_pk_add_f32 v[84:85], v[84:85], v[202:203]
	v_pk_add_f32 v[84:85], v[84:85], 1.0 op_sel_hi:[1,0]
	v_pk_add_f32 v[82:83], v[188:189], v[192:193]
	v_pk_add_f32 v[82:83], v[82:83], v[196:197]
	v_pk_add_f32 v[82:83], v[82:83], v[200:201]
	v_pk_add_f32 v[82:83], v[82:83], 1.0 op_sel_hi:[1,0]
	v_pk_add_f32 v[88:89], v[206:207], v[210:211]
	v_pk_add_f32 v[88:89], v[88:89], v[214:215]
	v_pk_add_f32 v[88:89], v[88:89], v[218:219]
	v_pk_add_f32 v[86:87], v[204:205], v[208:209]
	v_pk_add_f32 v[86:87], v[86:87], v[212:213]
	v_pk_add_f32 v[86:87], v[86:87], v[216:217]
.LBB0_132:
	s_and_b64 vcc, exec, s[38:39]
	s_cbranch_vccnz .LBB0_134
	global_load_dwordx4 v[188:191], v0, s[34:35] offset:2048
	s_add_u32 s54, s34, 0x30000
	s_addc_u32 s55, s35, 0
	global_load_dwordx4 v[192:195], v0, s[54:55] offset:2048
	s_add_u32 s56, s34, 0x60000
	s_addc_u32 s57, s35, 0
	global_load_dwordx4 v[196:199], v0, s[56:57] offset:2048
	s_add_u32 s62, s34, 0x90000
	s_addc_u32 s63, s35, 0
	global_load_dwordx4 v[200:203], v0, s[62:63] offset:2048
	global_load_dwordx4 v[18:21], v0, s[28:29] offset:2048
	s_waitcnt vmcnt(0)
	v_pk_add_f32 v[92:93], v[190:191], v[194:195]
	v_pk_add_f32 v[92:93], v[92:93], v[198:199]
	v_pk_add_f32 v[92:93], v[92:93], v[202:203]
	v_pk_add_f32 v[90:91], v[188:189], v[192:193]
	v_pk_add_f32 v[90:91], v[90:91], v[196:197]
	v_pk_add_f32 v[90:91], v[90:91], v[200:201]
.LBB0_134:
	s_and_b64 vcc, exec, s[40:41]
	s_cbranch_vccnz .LBB0_136
	global_load_dwordx4 v[188:191], v0, s[36:37] offset:2048
	s_add_u32 s54, s36, 0x30000
	s_addc_u32 s55, s37, 0
	global_load_dwordx4 v[192:195], v0, s[54:55] offset:2048
	s_mov_b32 s18, 0x60000
	global_load_dwordx4 v[22:25], v0, s[42:43] offset:2048
	s_add_u32 s56, s36, 0x60000
	s_addc_u32 s57, s37, 0
	global_load_dwordx4 v[196:199], v0, s[56:57] offset:2048
	s_add_u32 s62, s36, 0x90000
	s_addc_u32 s63, s37, 0
	global_load_dwordx4 v[200:203], v0, s[62:63] offset:2048
	global_load_dwordx4 v[204:207], v0, s[30:31] offset:2048
	s_add_u32 s54, s30, 0x30000
	s_addc_u32 s55, s31, 0
	global_load_dwordx4 v[208:211], v0, s[54:55] offset:2048
	s_add_u32 s56, s30, 0x60000
	s_addc_u32 s57, s31, 0
	global_load_dwordx4 v[212:215], v0, s[56:57] offset:2048
	s_mov_b32 s18, 0x90000
	s_add_u32 s62, s30, 0x90000
	s_addc_u32 s63, s31, 0
	global_load_dwordx4 v[216:219], v0, s[62:63] offset:2048
	s_waitcnt vmcnt(0)
	v_pk_add_f32 v[96:97], v[190:191], v[194:195]
	v_pk_add_f32 v[96:97], v[96:97], v[198:199]
	v_pk_add_f32 v[96:97], v[96:97], v[202:203]
	v_pk_add_f32 v[96:97], v[96:97], 1.0 op_sel_hi:[1,0]
	v_pk_add_f32 v[94:95], v[188:189], v[192:193]
	v_pk_add_f32 v[94:95], v[94:95], v[196:197]
	v_pk_add_f32 v[94:95], v[94:95], v[200:201]
	v_pk_add_f32 v[94:95], v[94:95], 1.0 op_sel_hi:[1,0]
	v_pk_add_f32 v[108:109], v[206:207], v[210:211]
	v_pk_add_f32 v[108:109], v[108:109], v[214:215]
	v_pk_add_f32 v[108:109], v[108:109], v[218:219]
	v_pk_add_f32 v[106:107], v[204:205], v[208:209]
	v_pk_add_f32 v[106:107], v[106:107], v[212:213]
	v_pk_add_f32 v[106:107], v[106:107], v[216:217]
.LBB0_136:
	s_and_b64 vcc, exec, s[38:39]
	s_cbranch_vccnz .LBB0_138
	global_load_dwordx4 v[188:191], v0, s[34:35] offset:3072
	s_add_u32 s54, s34, 0x30000
	s_addc_u32 s55, s35, 0
	global_load_dwordx4 v[192:195], v0, s[54:55] offset:3072
	s_add_u32 s56, s34, 0x60000
	s_addc_u32 s57, s35, 0
	global_load_dwordx4 v[196:199], v0, s[56:57] offset:3072
	s_add_u32 s62, s34, 0x90000
	s_addc_u32 s63, s35, 0
	global_load_dwordx4 v[200:203], v0, s[62:63] offset:3072
	global_load_dwordx4 v[26:29], v0, s[28:29] offset:3072
	s_waitcnt vmcnt(0)
	v_pk_add_f32 v[112:113], v[190:191], v[194:195]
	v_pk_add_f32 v[112:113], v[112:113], v[198:199]
	v_pk_add_f32 v[112:113], v[112:113], v[202:203]
	v_pk_add_f32 v[110:111], v[188:189], v[192:193]
	v_pk_add_f32 v[110:111], v[110:111], v[196:197]
	v_pk_add_f32 v[110:111], v[110:111], v[200:201]
.LBB0_138:
	s_and_b64 vcc, exec, s[40:41]
	s_cbranch_vccnz .LBB0_140
	global_load_dwordx4 v[188:191], v0, s[36:37] offset:3072
	s_add_u32 s54, s36, 0x30000
	s_addc_u32 s55, s37, 0
	global_load_dwordx4 v[192:195], v0, s[54:55] offset:3072
	s_mov_b32 s18, 0x60000
	global_load_dwordx4 v[30:33], v0, s[42:43] offset:3072
	s_add_u32 s56, s36, 0x60000
	s_addc_u32 s57, s37, 0
	global_load_dwordx4 v[196:199], v0, s[56:57] offset:3072
	s_add_u32 s62, s36, 0x90000
	s_addc_u32 s63, s37, 0
	global_load_dwordx4 v[200:203], v0, s[62:63] offset:3072
	global_load_dwordx4 v[204:207], v0, s[30:31] offset:3072
	s_add_u32 s54, s30, 0x30000
	s_addc_u32 s55, s31, 0
	global_load_dwordx4 v[208:211], v0, s[54:55] offset:3072
	s_add_u32 s56, s30, 0x60000
	s_addc_u32 s57, s31, 0
	global_load_dwordx4 v[212:215], v0, s[56:57] offset:3072
	s_mov_b32 s18, 0x90000
	s_add_u32 s62, s30, 0x90000
	s_addc_u32 s63, s31, 0
	global_load_dwordx4 v[216:219], v0, s[62:63] offset:3072
	s_waitcnt vmcnt(0)
	v_pk_add_f32 v[116:117], v[190:191], v[194:195]
	v_pk_add_f32 v[116:117], v[116:117], v[198:199]
	v_pk_add_f32 v[116:117], v[116:117], v[202:203]
	v_pk_add_f32 v[116:117], v[116:117], 1.0 op_sel_hi:[1,0]
	v_pk_add_f32 v[114:115], v[188:189], v[192:193]
	v_pk_add_f32 v[114:115], v[114:115], v[196:197]
	v_pk_add_f32 v[114:115], v[114:115], v[200:201]
	v_pk_add_f32 v[114:115], v[114:115], 1.0 op_sel_hi:[1,0]
	v_pk_add_f32 v[120:121], v[206:207], v[210:211]
	v_pk_add_f32 v[120:121], v[120:121], v[214:215]
	v_pk_add_f32 v[120:121], v[120:121], v[218:219]
	v_pk_add_f32 v[118:119], v[204:205], v[208:209]
	v_pk_add_f32 v[118:119], v[118:119], v[212:213]
	v_pk_add_f32 v[118:119], v[118:119], v[216:217]

.LBB0_148:
	s_and_b64 vcc, exec, s[38:39]
	s_cbranch_vccnz .LBB0_150
	s_waitcnt vmcnt(3)
	v_and_b32_e32 v151, 0xffff0000, v146
	s_waitcnt vmcnt(2)
	v_and_b32_e32 v150, 0xffff0000, v144
	v_lshlrev_b32_e32 v149, 16, v146
	v_lshlrev_b32_e32 v148, 16, v144
	v_pk_mul_f32 v[170:171], v[150:151], v[150:151]
	s_waitcnt vmcnt(1)
	v_and_b32_e32 v175, 0xffff0000, v142
	s_waitcnt vmcnt(0)
	v_and_b32_e32 v174, 0xffff0000, v140
	v_lshlrev_b32_e32 v153, 16, v147
	v_lshlrev_b32_e32 v152, 16, v145
	v_pk_fma_f32 v[170:171], v[148:149], v[148:149], v[170:171]
	v_lshlrev_b32_e32 v173, 16, v142
	v_lshlrev_b32_e32 v172, 16, v140
	v_pk_mul_f32 v[180:181], v[174:175], v[174:175]
	v_and_b32_e32 v169, 0xffff0000, v147
	v_and_b32_e32 v168, 0xffff0000, v145
	v_pk_fma_f32 v[170:171], v[152:153], v[152:153], v[170:171]
	v_lshlrev_b32_e32 v177, 16, v143
	v_lshlrev_b32_e32 v176, 16, v141
	v_pk_fma_f32 v[180:181], v[172:173], v[172:173], v[180:181]
	v_pk_fma_f32 v[170:171], v[168:169], v[168:169], v[170:171]
	v_and_b32_e32 v179, 0xffff0000, v143
	v_and_b32_e32 v178, 0xffff0000, v141
	v_pk_fma_f32 v[180:181], v[176:177], v[176:177], v[180:181]
	v_pk_fma_f32 v[180:181], v[178:179], v[178:179], v[180:181]
	v_add_f32_e32 v99, v170, v171
	v_add_f32_e32 v99, v181, v99
	v_add_f32_e32 v99, v180, v99
	s_nop 1
	v_add_f32_dpp v99, v99, v99 row_shr:1 row_mask:0xf bank_mask:0xf
	s_nop 1
	v_add_f32_dpp v99, v99, v99 row_shr:2 row_mask:0xf bank_mask:0xf
	s_nop 1
	v_add_f32_dpp v99, v99, v99 row_shr:4 row_mask:0xf bank_mask:0xf
	s_nop 1
	v_add_f32_dpp v99, v99, v99 row_shr:8 row_mask:0xf bank_mask:0xf
	s_nop 1
	v_readlane_b32 s54, v99, 15
	v_readlane_b32 s55, v99, 31
	v_readlane_b32 s56, v99, 47
	v_readlane_b32 s57, v99, 63
	s_nop 3
	v_mov_b32_e32 v99, s54
	v_add_f32_e32 v99, s55, v99
	v_add_f32_e32 v99, s56, v99
	v_add_f32_e32 v99, s57, v99
	v_mov_b32_e32 v182, v153
	v_mov_b32_e32 v184, v149
	v_mov_b32_e32 v153, v168
	v_mov_b32_e32 v149, v150
	v_mov_b32_e32 v185, v151
	v_mov_b32_e32 v183, v169
	v_lshl_add_u64 v[180:181], s[30:31], 0, v[0:1]
	v_fmamk_f32 v99, v99, 0x3a800000, v155
	v_mul_f32_e32 v101, 0x4b800000, v99
	v_cmp_gt_f32_e32 vcc, s84, v99
	s_nop 1
	v_cndmask_b32_e32 v99, v99, v101, vcc
	v_rsq_f32_e32 v99, v99
	s_nop 0
	v_mul_f32_e32 v101, 0x45800000, v99
	v_cndmask_b32_e32 v170, v99, v101, vcc
	v_pk_mul_f32 v[152:153], v[152:153], v[170:171] op_sel_hi:[1,0]
	v_pk_mul_f32 v[148:149], v[148:149], v[170:171] op_sel_hi:[1,0]
	v_pk_mul_f32 v[150:151], v[80:81], v[152:153]
	v_pk_mul_f32 v[148:149], v[78:79], v[148:149]
	v_pk_fma_f32 v[60:61], v[12:13], v[150:151], v[60:61]
	v_pk_fma_f32 v[58:59], v[10:11], v[148:149], v[58:59]
	v_mov_b32_e32 v148, v177
	v_mov_b32_e32 v149, v179
	v_mov_b32_e32 v150, v173
	v_mov_b32_e32 v151, v175
	v_pk_mul_f32 v[148:149], v[148:149], v[170:171] op_sel_hi:[1,0]
	v_pk_mul_f32 v[150:151], v[150:151], v[170:171] op_sel_hi:[1,0]
	v_pk_mul_f32 v[148:149], v[92:93], v[148:149]
	v_pk_mul_f32 v[150:151], v[90:91], v[150:151]
	v_mov_b32_e32 v177, v178
	v_mov_b32_e32 v173, v174
	v_pk_mul_f32 v[182:183], v[182:183], v[170:171] op_sel_hi:[1,0]
	v_pk_mul_f32 v[184:185], v[184:185], v[170:171] op_sel_hi:[1,0]
	v_pk_fma_f32 v[56:57], v[20:21], v[148:149], v[56:57]
	v_pk_fma_f32 v[54:55], v[18:19], v[150:151], v[54:55]
	v_pk_mul_f32 v[148:149], v[176:177], v[170:171] op_sel_hi:[1,0]
	v_pk_mul_f32 v[150:151], v[172:173], v[170:171] op_sel_hi:[1,0]
	v_pk_mul_f32 v[184:185], v[66:67], v[184:185]
	v_pk_mul_f32 v[182:183], v[68:69], v[182:183]
	v_pk_mul_f32 v[150:151], v[110:111], v[150:151]
	v_pk_mul_f32 v[148:149], v[112:113], v[148:149]
	v_pk_fma_f32 v[64:65], v[4:5], v[182:183], v[64:65]
	v_pk_fma_f32 v[62:63], v[2:3], v[184:185], v[62:63]
	v_pk_fma_f32 v[52:53], v[28:29], v[148:149], v[52:53]
	v_pk_fma_f32 v[50:51], v[26:27], v[150:151], v[50:51]
	global_store_dwordx4 v[180:181], v[62:65], off nt
	global_store_dwordx4 v[180:181], v[58:61], off offset:1024 nt
	global_store_dwordx4 v[180:181], v[54:57], off offset:2048 nt
	global_store_dwordx4 v[180:181], v[50:53], off offset:3072 nt
.LBB0_150:
	s_and_b64 vcc, exec, s[40:41]
	s_cbranch_vccnz .LBB0_152
	s_nop 1
	v_mov_b32_e32 v150, v59
	v_mov_b32_e32 v151, v63
	v_mov_b32_e32 v148, v58
	v_mov_b32_e32 v149, v62
	v_pk_mul_f32 v[150:151], v[150:151], v[150:151]
	s_nop 1
	v_mov_b32_e32 v152, v51
	v_pk_fma_f32 v[148:149], v[148:149], v[148:149], v[150:151]
	v_mov_b32_e32 v150, v60
	v_mov_b32_e32 v151, v64
	v_pk_fma_f32 v[148:149], v[150:151], v[150:151], v[148:149]
	v_mov_b32_e32 v150, v61
	v_mov_b32_e32 v151, v65
	v_mov_b32_e32 v153, v55
	v_pk_fma_f32 v[148:149], v[150:151], v[150:151], v[148:149]
	v_mov_b32_e32 v150, v50
	v_mov_b32_e32 v151, v54
	v_pk_mul_f32 v[152:153], v[152:153], v[152:153]
	v_pk_fma_f32 v[150:151], v[150:151], v[150:151], v[152:153]
	v_mov_b32_e32 v152, v52
	v_mov_b32_e32 v153, v56
	v_pk_fma_f32 v[150:151], v[152:153], v[152:153], v[150:151]
	v_mov_b32_e32 v152, v53
	v_mov_b32_e32 v153, v57
	v_pk_fma_f32 v[150:151], v[152:153], v[152:153], v[150:151]
	v_add_f32_e32 v99, v148, v149
	v_add_f32_e32 v99, v151, v99
	v_add_f32_e32 v99, v150, v99
	s_nop 1
	v_add_f32_dpp v99, v99, v99 row_shr:1 row_mask:0xf bank_mask:0xf
	s_nop 1
	v_add_f32_dpp v99, v99, v99 row_shr:2 row_mask:0xf bank_mask:0xf
	s_nop 1
	v_add_f32_dpp v99, v99, v99 row_shr:4 row_mask:0xf bank_mask:0xf
	s_nop 1
	v_add_f32_dpp v99, v99, v99 row_shr:8 row_mask:0xf bank_mask:0xf
	s_nop 1
	v_readlane_b32 s54, v99, 15
	v_readlane_b32 s55, v99, 31
	v_readlane_b32 s56, v99, 47
	v_readlane_b32 s57, v99, 63
	s_nop 3
	v_mov_b32_e32 v99, s54
	v_add_f32_e32 v99, s55, v99
	v_add_f32_e32 v99, s56, v99
	v_add_f32_e32 v99, s57, v99
	v_lshl_add_u64 v[150:151], s[26:27], 0, v[130:131]
	v_fmamk_f32 v99, v99, 0x3a800000, v155
	v_mul_f32_e32 v101, 0x4b800000, v99
	v_cmp_gt_f32_e32 vcc, s84, v99
	s_nop 1
	v_cndmask_b32_e32 v99, v99, v101, vcc
	v_rsq_f32_e32 v99, v99
	s_nop 0
	v_mul_f32_e32 v101, 0x45800000, v99
	v_cndmask_b32_e32 v148, v99, v101, vcc
	v_pk_mul_f32 v[64:65], v[64:65], v[148:149] op_sel_hi:[1,0]
	v_pk_mul_f32 v[62:63], v[62:63], v[148:149] op_sel_hi:[1,0]
	v_pk_mul_f32 v[60:61], v[60:61], v[148:149] op_sel_hi:[1,0]
	v_pk_mul_f32 v[58:59], v[58:59], v[148:149] op_sel_hi:[1,0]
	v_pk_mul_f32 v[56:57], v[56:57], v[148:149] op_sel_hi:[1,0]
	v_pk_mul_f32 v[54:55], v[54:55], v[148:149] op_sel_hi:[1,0]
	v_pk_mul_f32 v[52:53], v[52:53], v[148:149] op_sel_hi:[1,0]
	v_pk_mul_f32 v[50:51], v[50:51], v[148:149] op_sel_hi:[1,0]
	v_pk_mul_f32 v[62:63], v[6:7], v[62:63]
	v_pk_mul_f32 v[64:65], v[8:9], v[64:65]
	v_pk_mul_f32 v[58:59], v[14:15], v[58:59]
	v_pk_mul_f32 v[60:61], v[16:17], v[60:61]
	v_pk_mul_f32 v[54:55], v[22:23], v[54:55]
	v_pk_mul_f32 v[56:57], v[24:25], v[56:57]
	v_pk_mul_f32 v[50:51], v[30:31], v[50:51]
	v_pk_mul_f32 v[52:53], v[32:33], v[52:53]
	v_pk_fma_f32 v[64:65], v[72:73], v[64:65], v[76:77]
	v_pk_fma_f32 v[62:63], v[70:71], v[62:63], v[74:75]
	v_pk_fma_f32 v[60:61], v[84:85], v[60:61], v[88:89]
	v_pk_fma_f32 v[58:59], v[82:83], v[58:59], v[86:87]
	v_pk_fma_f32 v[56:57], v[96:97], v[56:57], v[108:109]
	v_pk_fma_f32 v[54:55], v[94:95], v[54:55], v[106:107]
	v_pk_fma_f32 v[52:53], v[116:117], v[52:53], v[120:121]
	v_pk_fma_f32 v[50:51], v[114:115], v[50:51], v[118:119]
	v_cvt_pk_bf16_f32 v62, v62, v63
	v_cvt_pk_bf16_f32 v63, v64, v65
	v_cvt_pk_bf16_f32 v58, v58, v59
	v_cvt_pk_bf16_f32 v59, v60, v61
	v_cvt_pk_bf16_f32 v54, v54, v55
	v_cvt_pk_bf16_f32 v55, v56, v57
	v_cvt_pk_bf16_f32 v50, v50, v51
	v_cvt_pk_bf16_f32 v51, v52, v53
	v_readlane_b32 vcc_lo, v244, 60
	v_readlane_b32 vcc_hi, v244, 61
	s_nop 3
	v_subrev_u32_e32 v64, vcc_lo, v150
	v_and_b32_e32 v60, 0x7ff, v64
	v_lshrrev_b32_e32 v64, 11, v64
	v_lshlrev_b32_e32 v64, 6, v64
	v_lshrrev_b32_e32 v61, 6, v60
	v_lshl_or_b32 v64, v61, 20, v64
	v_and_or_b32 v64, v60, 63, v64
	v_mov_b32_e32 v65, 0
	v_lshl_add_u64 v[64:65], vcc, 0, v[64:65]
	global_store_dwordx2 v[64:65], v[62:63], off
	v_subrev_u32_e32 v64, vcc_lo, v150
	v_add_u32_e32 v64, 0x200, v64
	v_and_b32_e32 v60, 0x7ff, v64
	v_lshrrev_b32_e32 v64, 11, v64
	v_lshlrev_b32_e32 v64, 6, v64
	v_lshrrev_b32_e32 v61, 6, v60
	v_lshl_or_b32 v64, v61, 20, v64
	v_and_or_b32 v64, v60, 63, v64
	v_mov_b32_e32 v65, 0
	v_lshl_add_u64 v[64:65], vcc, 0, v[64:65]
	global_store_dwordx2 v[64:65], v[58:59], off
	v_subrev_u32_e32 v64, vcc_lo, v150
	v_add_u32_e32 v64, 0x400, v64
	v_and_b32_e32 v60, 0x7ff, v64
	v_lshrrev_b32_e32 v64, 11, v64
	v_lshlrev_b32_e32 v64, 6, v64
	v_lshrrev_b32_e32 v61, 6, v60
	v_lshl_or_b32 v64, v61, 20, v64
	v_and_or_b32 v64, v60, 63, v64
	v_mov_b32_e32 v65, 0
	v_lshl_add_u64 v[64:65], vcc, 0, v[64:65]
	global_store_dwordx2 v[64:65], v[54:55], off
	v_subrev_u32_e32 v64, vcc_lo, v150
	v_add_u32_e32 v64, 0x600, v64
	v_and_b32_e32 v60, 0x7ff, v64
	v_lshrrev_b32_e32 v64, 11, v64
	v_lshlrev_b32_e32 v64, 6, v64
	v_lshrrev_b32_e32 v61, 6, v60
	v_lshl_or_b32 v64, v61, 20, v64
	v_and_or_b32 v64, v60, 63, v64
	v_mov_b32_e32 v65, 0
	v_lshl_add_u64 v[64:65], vcc, 0, v[64:65]
	global_store_dwordx2 v[64:65], v[50:51], off
.LBB0_152:
	s_andn2_b64 vcc, exec, s[36:37]
	s_cbranch_vccnz .LBB0_142
	s_and_b64 vcc, exec, s[38:39]
	s_cbranch_vccnz .LBB0_155
	s_nop 1
	v_and_b32_e32 v53, 0xffff0000, v138
	v_and_b32_e32 v52, 0xffff0000, v136
	v_lshlrev_b32_e32 v51, 16, v138
	v_lshlrev_b32_e32 v50, 16, v136
	v_pk_mul_f32 v[58:59], v[52:53], v[52:53]
	v_lshlrev_b32_e32 v55, 16, v139
	v_lshlrev_b32_e32 v54, 16, v137
	v_pk_fma_f32 v[58:59], v[50:51], v[50:51], v[58:59]
	v_and_b32_e32 v57, 0xffff0000, v139
	v_and_b32_e32 v56, 0xffff0000, v137
	v_pk_fma_f32 v[58:59], v[54:55], v[54:55], v[58:59]
	v_and_b32_e32 v63, 0xffff0000, v134
	v_and_b32_e32 v62, 0xffff0000, v132
	v_pk_fma_f32 v[58:59], v[56:57], v[56:57], v[58:59]
	v_lshlrev_b32_e32 v61, 16, v134
	v_lshlrev_b32_e32 v60, 16, v132
	v_pk_mul_f32 v[150:151], v[62:63], v[62:63]
	v_lshlrev_b32_e32 v65, 16, v135
	v_lshlrev_b32_e32 v64, 16, v133
	v_pk_fma_f32 v[150:151], v[60:61], v[60:61], v[150:151]
	v_add_f32_e32 v58, v58, v59
	v_and_b32_e32 v149, 0xffff0000, v135
	v_and_b32_e32 v148, 0xffff0000, v133
	v_pk_fma_f32 v[150:151], v[64:65], v[64:65], v[150:151]
	v_pk_fma_f32 v[150:151], v[148:149], v[148:149], v[150:151]
	v_add_f32_e32 v58, v151, v58
	v_add_f32_e32 v58, v150, v58
	s_nop 1
	v_add_f32_dpp v58, v58, v58 row_shr:1 row_mask:0xf bank_mask:0xf
	s_nop 1
	v_add_f32_dpp v58, v58, v58 row_shr:2 row_mask:0xf bank_mask:0xf
	s_nop 1
	v_add_f32_dpp v58, v58, v58 row_shr:4 row_mask:0xf bank_mask:0xf
	s_nop 1
	v_add_f32_dpp v58, v58, v58 row_shr:8 row_mask:0xf bank_mask:0xf
	s_nop 1
	v_readlane_b32 s54, v58, 15
	v_readlane_b32 s55, v58, 31
	v_readlane_b32 s56, v58, 47
	v_readlane_b32 s57, v58, 63
	s_nop 3
	v_mov_b32_e32 v58, s54
	v_add_f32_e32 v58, s55, v58
	v_add_f32_e32 v58, s56, v58
	v_add_f32_e32 v58, s57, v58
	v_mov_b32_e32 v152, v55
	v_mov_b32_e32 v168, v51
	v_mov_b32_e32 v55, v56
	v_mov_b32_e32 v51, v52
	v_mov_b32_e32 v169, v53
	v_mov_b32_e32 v153, v57
	s_ashr_i32 s35, s34, 31
	s_lshl_b64 s[20:21], s[34:35], 12
	v_lshl_add_u64 v[150:151], v[126:127], 0, s[20:21]
	v_fmamk_f32 v58, v58, 0x3a800000, v155
	v_mul_f32_e32 v59, 0x4b800000, v58
	v_cmp_gt_f32_e32 vcc, s84, v58
	s_nop 1
	v_cndmask_b32_e32 v58, v58, v59, vcc
	v_rsq_f32_e32 v58, v58
	s_nop 0
	v_mul_f32_e32 v59, 0x45800000, v58
	v_cndmask_b32_e32 v58, v58, v59, vcc
	v_pk_mul_f32 v[54:55], v[54:55], v[58:59] op_sel_hi:[1,0]
	v_pk_mul_f32 v[50:51], v[50:51], v[58:59] op_sel_hi:[1,0]
	v_pk_mul_f32 v[52:53], v[80:81], v[54:55]
	v_pk_mul_f32 v[50:51], v[78:79], v[50:51]
	v_pk_fma_f32 v[40:41], v[12:13], v[52:53], v[40:41]
	v_pk_fma_f32 v[38:39], v[10:11], v[50:51], v[38:39]
	v_mov_b32_e32 v50, v65
	v_mov_b32_e32 v51, v149
	v_mov_b32_e32 v52, v61
	v_mov_b32_e32 v53, v63
	v_pk_mul_f32 v[50:51], v[50:51], v[58:59] op_sel_hi:[1,0]
	v_pk_mul_f32 v[52:53], v[52:53], v[58:59] op_sel_hi:[1,0]
	v_pk_mul_f32 v[50:51], v[92:93], v[50:51]
	v_pk_mul_f32 v[52:53], v[90:91], v[52:53]
	v_mov_b32_e32 v65, v148
	v_mov_b32_e32 v61, v62
	v_pk_mul_f32 v[152:153], v[152:153], v[58:59] op_sel_hi:[1,0]
	v_pk_mul_f32 v[168:169], v[168:169], v[58:59] op_sel_hi:[1,0]
	v_pk_fma_f32 v[44:45], v[20:21], v[50:51], v[44:45]
	v_pk_fma_f32 v[42:43], v[18:19], v[52:53], v[42:43]
	v_pk_mul_f32 v[50:51], v[64:65], v[58:59] op_sel_hi:[1,0]
	v_pk_mul_f32 v[52:53], v[60:61], v[58:59] op_sel_hi:[1,0]
	v_pk_mul_f32 v[168:169], v[66:67], v[168:169]
	v_pk_mul_f32 v[152:153], v[68:69], v[152:153]
	v_pk_mul_f32 v[52:53], v[110:111], v[52:53]
	v_pk_mul_f32 v[50:51], v[112:113], v[50:51]
	v_pk_fma_f32 v[36:37], v[4:5], v[152:153], v[36:37]
	v_pk_fma_f32 v[34:35], v[2:3], v[168:169], v[34:35]
	v_pk_fma_f32 v[48:49], v[28:29], v[50:51], v[48:49]
	v_pk_fma_f32 v[46:47], v[26:27], v[52:53], v[46:47]
	global_store_dwordx4 v[150:151], v[34:37], off nt
	global_store_dwordx4 v[150:151], v[38:41], off offset:1024 nt
	global_store_dwordx4 v[150:151], v[42:45], off offset:2048 nt
	global_store_dwordx4 v[150:151], v[46:49], off offset:3072 nt
.LBB0_155:
	s_and_b64 vcc, exec, s[40:41]
	s_cbranch_vccnz .LBB0_142
	s_nop 1
	v_mov_b32_e32 v52, v39
	v_mov_b32_e32 v53, v35
	v_mov_b32_e32 v50, v38
	v_mov_b32_e32 v51, v34
	v_pk_mul_f32 v[52:53], v[52:53], v[52:53]
	v_mov_b32_e32 v54, v47
	v_pk_fma_f32 v[50:51], v[50:51], v[50:51], v[52:53]
	v_mov_b32_e32 v52, v40
	v_mov_b32_e32 v53, v36
	v_pk_fma_f32 v[50:51], v[52:53], v[52:53], v[50:51]
	v_mov_b32_e32 v52, v41
	v_mov_b32_e32 v53, v37
	v_mov_b32_e32 v55, v43
	v_pk_fma_f32 v[50:51], v[52:53], v[52:53], v[50:51]
	v_mov_b32_e32 v52, v46
	v_mov_b32_e32 v53, v42
	v_pk_mul_f32 v[54:55], v[54:55], v[54:55]
	v_add_f32_e32 v50, v50, v51
	v_pk_fma_f32 v[52:53], v[52:53], v[52:53], v[54:55]
	v_mov_b32_e32 v54, v48
	v_mov_b32_e32 v55, v44
	v_pk_fma_f32 v[52:53], v[54:55], v[54:55], v[52:53]
	v_mov_b32_e32 v54, v49
	v_mov_b32_e32 v55, v45
	v_pk_fma_f32 v[52:53], v[54:55], v[54:55], v[52:53]
	v_add_f32_e32 v50, v53, v50
	v_add_f32_e32 v50, v52, v50
	s_ashr_i32 s35, s34, 31
	s_lshl_b64 s[20:21], s[34:35], 11
	s_nop 1
	v_add_f32_dpp v50, v50, v50 row_shr:1 row_mask:0xf bank_mask:0xf
	s_nop 1
	v_add_f32_dpp v50, v50, v50 row_shr:2 row_mask:0xf bank_mask:0xf
	s_nop 1
	v_add_f32_dpp v50, v50, v50 row_shr:4 row_mask:0xf bank_mask:0xf
	s_nop 1
	v_add_f32_dpp v50, v50, v50 row_shr:8 row_mask:0xf bank_mask:0xf
	s_nop 1
	v_readlane_b32 s54, v50, 15
	v_readlane_b32 s55, v50, 31
	v_readlane_b32 s56, v50, 47
	v_readlane_b32 s57, v50, 63
	s_nop 3
	v_mov_b32_e32 v50, s54
	v_add_f32_e32 v50, s55, v50
	v_add_f32_e32 v50, s56, v50
	v_add_f32_e32 v50, s57, v50
	v_lshl_add_u64 v[52:53], v[128:129], 0, s[20:21]
	v_fmamk_f32 v50, v50, 0x3a800000, v155
	v_mul_f32_e32 v51, 0x4b800000, v50
	v_cmp_gt_f32_e32 vcc, s84, v50
	s_nop 1
	v_cndmask_b32_e32 v50, v50, v51, vcc
	v_rsq_f32_e32 v50, v50
	s_nop 0
	v_mul_f32_e32 v51, 0x45800000, v50
	v_cndmask_b32_e32 v50, v50, v51, vcc
	v_pk_mul_f32 v[54:55], v[36:37], v[50:51] op_sel_hi:[1,0]
	v_pk_mul_f32 v[56:57], v[34:35], v[50:51] op_sel_hi:[1,0]
	v_pk_mul_f32 v[54:55], v[8:9], v[54:55]
	v_pk_mul_f32 v[56:57], v[6:7], v[56:57]
	v_pk_fma_f32 v[54:55], v[72:73], v[54:55], v[76:77]
	v_pk_fma_f32 v[56:57], v[70:71], v[56:57], v[74:75]
	s_nop 0
	v_cvt_pk_bf16_f32 v56, v56, v57
	v_cvt_pk_bf16_f32 v57, v54, v55
	v_readlane_b32 vcc_lo, v244, 60
	v_readlane_b32 vcc_hi, v244, 61
	s_nop 3
	v_subrev_u32_e32 v34, vcc_lo, v52
	v_and_b32_e32 v36, 0x7ff, v34
	v_lshrrev_b32_e32 v34, 11, v34
	v_lshlrev_b32_e32 v34, 6, v34
	v_lshrrev_b32_e32 v37, 6, v36
	v_lshl_or_b32 v34, v37, 20, v34
	v_and_or_b32 v34, v36, 63, v34
	v_mov_b32_e32 v35, 0
	v_lshl_add_u64 v[34:35], vcc, 0, v[34:35]
	global_store_dwordx2 v[34:35], v[56:57], off
	v_pk_mul_f32 v[54:55], v[40:41], v[50:51] op_sel_hi:[1,0]
	v_pk_mul_f32 v[56:57], v[38:39], v[50:51] op_sel_hi:[1,0]
	v_pk_mul_f32 v[54:55], v[16:17], v[54:55]
	v_pk_mul_f32 v[56:57], v[14:15], v[56:57]
	v_pk_fma_f32 v[54:55], v[84:85], v[54:55], v[88:89]
	v_pk_fma_f32 v[56:57], v[82:83], v[56:57], v[86:87]
	s_nop 0
	v_cvt_pk_bf16_f32 v56, v56, v57
	v_cvt_pk_bf16_f32 v57, v54, v55
	v_subrev_u32_e32 v34, vcc_lo, v52
	v_add_u32_e32 v34, 0x200, v34
	v_and_b32_e32 v36, 0x7ff, v34
	v_lshrrev_b32_e32 v34, 11, v34
	v_lshlrev_b32_e32 v34, 6, v34
	v_lshrrev_b32_e32 v37, 6, v36
	v_lshl_or_b32 v34, v37, 20, v34
	v_and_or_b32 v34, v36, 63, v34
	v_mov_b32_e32 v35, 0
	v_lshl_add_u64 v[34:35], vcc, 0, v[34:35]
	global_store_dwordx2 v[34:35], v[56:57], off
	v_pk_mul_f32 v[54:55], v[44:45], v[50:51] op_sel_hi:[1,0]
	v_pk_mul_f32 v[56:57], v[42:43], v[50:51] op_sel_hi:[1,0]
	v_pk_mul_f32 v[54:55], v[24:25], v[54:55]
	v_pk_mul_f32 v[56:57], v[22:23], v[56:57]
	v_pk_fma_f32 v[54:55], v[96:97], v[54:55], v[108:109]
	v_pk_fma_f32 v[56:57], v[94:95], v[56:57], v[106:107]
	s_nop 0
	v_cvt_pk_bf16_f32 v56, v56, v57
	v_cvt_pk_bf16_f32 v57, v54, v55
	v_pk_mul_f32 v[54:55], v[48:49], v[50:51] op_sel_hi:[1,0]
	v_pk_mul_f32 v[50:51], v[46:47], v[50:51] op_sel_hi:[1,0]
	v_pk_mul_f32 v[54:55], v[32:33], v[54:55]
	v_pk_mul_f32 v[50:51], v[30:31], v[50:51]
	v_pk_fma_f32 v[54:55], v[116:117], v[54:55], v[120:121]
	v_pk_fma_f32 v[50:51], v[114:115], v[50:51], v[118:119]
	v_subrev_u32_e32 v34, vcc_lo, v52
	v_add_u32_e32 v34, 0x400, v34
	v_and_b32_e32 v36, 0x7ff, v34
	v_lshrrev_b32_e32 v34, 11, v34
	v_lshlrev_b32_e32 v34, 6, v34
	v_lshrrev_b32_e32 v37, 6, v36
	v_lshl_or_b32 v34, v37, 20, v34
	v_and_or_b32 v34, v36, 63, v34
	v_mov_b32_e32 v35, 0
	v_lshl_add_u64 v[34:35], vcc, 0, v[34:35]
	global_store_dwordx2 v[34:35], v[56:57], off
	v_cvt_pk_bf16_f32 v50, v50, v51
	v_cvt_pk_bf16_f32 v51, v54, v55
	v_subrev_u32_e32 v34, vcc_lo, v52
	v_add_u32_e32 v34, 0x600, v34
	v_and_b32_e32 v36, 0x7ff, v34
	v_lshrrev_b32_e32 v34, 11, v34
	v_lshlrev_b32_e32 v34, 6, v34
	v_lshrrev_b32_e32 v37, 6, v36
	v_lshl_or_b32 v34, v37, 20, v34
	v_and_or_b32 v34, v36, 63, v34
	v_mov_b32_e32 v35, 0
	v_lshl_add_u64 v[34:35], vcc, 0, v[34:35]
	global_store_dwordx2 v[34:35], v[50:51], off
	s_branch .LBB0_142

.LBB0_190:
	v_and_b32_e32 v28, 64, v159
	v_xor_b32_e32 v27, 16, v159
	v_add_u32_e32 v28, 64, v28
	v_cmp_lt_i32_e32 vcc, v27, v28
	v_and_b32_e32 v0, 63, v26
	s_mov_b64 s[40:41], src_shared_base
	v_cndmask_b32_e32 v27, v159, v27, vcc
	v_lshlrev_b32_e32 v65, 2, v27
	v_xor_b32_e32 v27, 32, v159
	s_add_i32 s38, s38, s66
	v_cmp_lt_i32_e32 vcc, v27, v28
	v_bfe_u32 v55, v26, 4, 2
	s_mov_b32 s7, s41
	v_or_b32_e32 v43, s38, v68
	v_cndmask_b32_e32 v27, v159, v27, vcc
	v_and_b32_e32 v26, 16, v26
	v_cmp_gt_u32_e64 s[38:39], 32, v0
	v_cmp_eq_u32_e64 s[40:41], 0, v0
	v_mad_u32_u24 v0, v68, s98, v42
	v_lshlrev_b32_e32 v69, 2, v27
	v_cmp_eq_u32_e32 vcc, 0, v26
	ds_read_b128 v[26:29], v0
	ds_read_b128 v[30:33], v0 offset:64
	s_waitcnt vmcnt(1) lgkmcnt(1)
	v_mfma_f32_16x16x32_bf16 v[26:29], v[26:29], v[6:9], 0
	ds_read_b128 v[34:37], v0 offset:2368
	s_lshl_b32 s6, s6, 2
	ds_read_b128 v[38:41], v0 offset:4672
	s_waitcnt vmcnt(0) lgkmcnt(2)
	v_mfma_f32_16x16x32_bf16 v[26:29], v[30:33], v[10:13], v[26:29]
	ds_read_b128 v[30:33], v0 offset:2304
	s_addk_i32 s6, 0x4800
	s_mov_b64 s[92:93], exec
	s_waitcnt lgkmcnt(0)
	v_mfma_f32_16x16x32_bf16 v[30:33], v[30:33], v[6:9], 0
	ds_read_b128 v[44:47], v0 offset:6976
	v_mfma_f32_16x16x32_bf16 v[30:33], v[34:37], v[10:13], v[30:33]
	ds_read_b128 v[34:37], v0 offset:4608
	s_waitcnt lgkmcnt(0)
	v_mfma_f32_16x16x32_bf16 v[34:37], v[34:37], v[6:9], 0
	v_mfma_f32_16x16x32_bf16 v[34:37], v[38:41], v[10:13], v[34:37]
	ds_read_b128 v[38:41], v0 offset:6912
	v_lshl_or_b32 v0, v55, 2, s66
	v_cmp_lt_i32_e64 s[42:43], v0, v43
	s_waitcnt lgkmcnt(0)
	v_mfma_f32_16x16x32_bf16 v[38:41], v[38:41], v[6:9], 0
	v_mfma_f32_16x16x32_bf16 v[38:41], v[44:47], v[10:13], v[38:41]
	v_exp_f32_e64 v45, -|v26|
	v_exp_f32_e64 v46, -|v27|
	v_max_f32_e32 v44, v26, v26
	v_max_f32_e32 v44, 0, v44
	v_add_f32_e32 v45, 1.0, v45
	v_log_f32_e32 v45, v45
	v_add_f32_e32 v46, 1.0, v46
	v_log_f32_e32 v46, v46
	v_add_f32_e32 v44, v44, v45
	v_sub_f32_e32 v26, v26, v44
	v_cndmask_b32_e64 v45, 0, -v44, s[42:43]
	v_cndmask_b32_e64 v44, v163, v26, s[42:43]
	v_max_f32_e32 v26, v27, v27
	v_max_f32_e32 v26, 0, v26
	v_add_f32_e32 v26, v26, v46
	v_or_b32_e32 v46, 1, v0
	v_cmp_lt_i32_e64 s[42:43], v46, v43
	s_nop 1
	v_cndmask_b32_e64 v46, 0, -v26, s[42:43]
	v_sub_f32_e32 v26, v27, v26
	v_exp_f32_e64 v27, -|v28|
	v_cndmask_b32_e64 v47, v163, v26, s[42:43]
	v_max_f32_e32 v26, v28, v28
	v_max_f32_e32 v26, 0, v26
	v_add_f32_e32 v27, 1.0, v27
	v_log_f32_e32 v27, v27
	s_nop 0
	v_add_f32_e32 v26, v26, v27
	v_or_b32_e32 v27, 2, v0
	v_cmp_lt_i32_e64 s[42:43], v27, v43
	v_exp_f32_e64 v27, -|v29|
	s_nop 0
	v_cndmask_b32_e64 v48, 0, -v26, s[42:43]
	v_sub_f32_e32 v26, v28, v26
	v_add_f32_e32 v27, 1.0, v27
	v_exp_f32_e64 v28, -|v30|
	v_log_f32_e32 v27, v27
	v_cndmask_b32_e64 v49, v163, v26, s[42:43]
	v_max_f32_e32 v26, v29, v29
	v_max_f32_e32 v26, 0, v26
	v_add_f32_e32 v28, 1.0, v28
	v_add_f32_e32 v26, v26, v27
	v_or_b32_e32 v27, 3, v0
	v_log_f32_e32 v28, v28
	v_cmp_lt_i32_e64 s[42:43], v27, v43
	v_max_f32_e32 v27, v30, v30
	v_max_f32_e32 v27, 0, v27
	v_cndmask_b32_e64 v50, 0, -v26, s[42:43]
	v_sub_f32_e32 v26, v29, v26
	v_cndmask_b32_e64 v51, v163, v26, s[42:43]
	v_or_b32_e32 v26, 16, v0
	v_add_f32_e32 v27, v27, v28
	v_cmp_lt_i32_e64 s[42:43], v26, v43
	v_sub_f32_e32 v26, v30, v27
	v_exp_f32_e64 v28, -|v34|
	v_cndmask_b32_e64 v29, 0, -v27, s[42:43]
	v_exp_f32_e64 v27, -|v31|
	v_cndmask_b32_e64 v52, v163, v26, s[42:43]
	v_max_f32_e32 v26, v31, v31
	v_max_f32_e32 v26, 0, v26
	v_add_f32_e32 v27, 1.0, v27
	v_log_f32_e32 v27, v27
	v_add_f32_e32 v28, 1.0, v28
	v_log_f32_e32 v28, v28
	v_add_f32_e32 v26, v26, v27
	v_or_b32_e32 v27, 17, v0
	v_cmp_lt_i32_e64 s[42:43], v27, v43
	v_exp_f32_e64 v27, -|v32|
	s_nop 0
	v_cndmask_b32_e64 v53, 0, -v26, s[42:43]
	v_sub_f32_e32 v26, v31, v26
	v_add_f32_e32 v27, 1.0, v27
	v_log_f32_e32 v27, v27
	v_cndmask_b32_e64 v66, v163, v26, s[42:43]
	v_max_f32_e32 v26, v32, v32
	v_max_f32_e32 v26, 0, v26
	v_add_f32_e32 v26, v26, v27
	v_or_b32_e32 v27, 18, v0
	v_cmp_lt_i32_e64 s[42:43], v27, v43
	v_exp_f32_e64 v27, -|v33|
	s_nop 0
	v_cndmask_b32_e64 v67, 0, -v26, s[42:43]
	v_sub_f32_e32 v26, v32, v26
	v_add_f32_e32 v27, 1.0, v27
	v_log_f32_e32 v27, v27
	v_cndmask_b32_e64 v70, v163, v26, s[42:43]
	v_max_f32_e32 v26, v33, v33
	v_max_f32_e32 v26, 0, v26
	v_add_f32_e32 v26, v26, v27
	v_or_b32_e32 v27, 19, v0
	v_cmp_lt_i32_e64 s[42:43], v27, v43
	v_max_f32_e32 v27, v34, v34
	v_max_f32_e32 v27, 0, v27
	v_cndmask_b32_e64 v71, 0, -v26, s[42:43]
	v_sub_f32_e32 v26, v33, v26
	v_cndmask_b32_e64 v72, v163, v26, s[42:43]
	v_or_b32_e32 v26, 32, v0
	v_add_f32_e32 v27, v27, v28
	v_cmp_lt_i32_e64 s[42:43], v26, v43
	v_sub_f32_e32 v26, v34, v27
	v_exp_f32_e64 v28, -|v38|
	v_cndmask_b32_e64 v31, 0, -v27, s[42:43]
	v_exp_f32_e64 v27, -|v35|
	v_cndmask_b32_e64 v33, v163, v26, s[42:43]
	v_max_f32_e32 v26, v35, v35
	v_max_f32_e32 v26, 0, v26
	v_add_f32_e32 v27, 1.0, v27
	v_log_f32_e32 v27, v27
	v_add_f32_e32 v28, 1.0, v28
	v_log_f32_e32 v28, v28
	v_add_f32_e32 v26, v26, v27
	v_or_b32_e32 v27, 33, v0
	v_cmp_lt_i32_e64 s[42:43], v27, v43
	v_exp_f32_e64 v27, -|v36|
	s_nop 0
	v_cndmask_b32_e64 v73, 0, -v26, s[42:43]
	v_sub_f32_e32 v26, v35, v26
	v_add_f32_e32 v27, 1.0, v27
	v_log_f32_e32 v27, v27
	v_cndmask_b32_e64 v74, v163, v26, s[42:43]
	v_max_f32_e32 v26, v36, v36
	v_max_f32_e32 v26, 0, v26
	v_add_f32_e32 v26, v26, v27
	v_or_b32_e32 v27, 34, v0
	v_cmp_lt_i32_e64 s[42:43], v27, v43
	v_exp_f32_e64 v27, -|v37|
	s_nop 0
	v_cndmask_b32_e64 v75, 0, -v26, s[42:43]
	v_sub_f32_e32 v26, v36, v26
	v_add_f32_e32 v27, 1.0, v27
	v_log_f32_e32 v27, v27
	v_cndmask_b32_e64 v36, v163, v26, s[42:43]
	v_max_f32_e32 v26, v37, v37
	v_max_f32_e32 v26, 0, v26
	v_add_f32_e32 v26, v26, v27
	v_or_b32_e32 v27, 35, v0
	v_cmp_lt_i32_e64 s[42:43], v27, v43
	v_max_f32_e32 v27, v38, v38
	v_max_f32_e32 v27, 0, v27
	v_cndmask_b32_e64 v76, 0, -v26, s[42:43]
	v_sub_f32_e32 v26, v37, v26
	v_cndmask_b32_e64 v37, v163, v26, s[42:43]
	v_or_b32_e32 v26, 48, v0
	v_add_f32_e32 v27, v27, v28
	v_cmp_lt_i32_e64 s[42:43], v26, v43
	v_sub_f32_e32 v26, v38, v27
	s_nop 0
	v_cndmask_b32_e64 v35, 0, -v27, s[42:43]
	v_exp_f32_e64 v27, -|v39|
	v_cndmask_b32_e64 v38, v163, v26, s[42:43]
	v_max_f32_e32 v26, v39, v39
	v_max_f32_e32 v26, 0, v26
	v_add_f32_e32 v27, 1.0, v27
	v_log_f32_e32 v27, v27
	s_nop 0
	v_add_f32_e32 v26, v26, v27
	v_or_b32_e32 v27, 49, v0
	v_cmp_lt_i32_e64 s[42:43], v27, v43
	v_exp_f32_e64 v27, -|v40|
	s_nop 0
	v_cndmask_b32_e64 v77, 0, -v26, s[42:43]
	v_sub_f32_e32 v26, v39, v26
	v_add_f32_e32 v27, 1.0, v27
	v_log_f32_e32 v27, v27
	v_cndmask_b32_e64 v39, v163, v26, s[42:43]
	v_max_f32_e32 v26, v40, v40
	v_max_f32_e32 v26, 0, v26
	v_add_f32_e32 v26, v26, v27
	v_or_b32_e32 v27, 50, v0
	v_cmp_lt_i32_e64 s[42:43], v27, v43
	v_exp_f32_e64 v27, -|v41|
	v_or_b32_e32 v0, 51, v0
	v_cndmask_b32_e64 v78, 0, -v26, s[42:43]
	v_sub_f32_e32 v26, v40, v26
	v_add_f32_e32 v27, 1.0, v27
	v_log_f32_e32 v27, v27
	v_cndmask_b32_e64 v40, v163, v26, s[42:43]
	v_max_f32_e32 v26, v41, v41
	v_max_f32_e32 v26, 0, v26
	v_add_f32_e32 v26, v26, v27
	v_cmp_lt_i32_e64 s[42:43], v0, v43
	v_sub_f32_e32 v0, v41, v26
	s_nop 0
	v_cndmask_b32_e64 v43, 0, -v26, s[42:43]
	v_cndmask_b32_e64 v41, v163, v0, s[42:43]
	v_add_f32_e32 v0, v45, v46
	v_add_f32_e32 v26, v48, v50
	v_add_f32_e32 v0, v0, v26
	ds_bpermute_b32 v26, v65, v0
	s_waitcnt lgkmcnt(0)
	v_add_f32_e32 v0, v0, v26
	ds_bpermute_b32 v27, v69, v0
	v_cndmask_b32_e32 v26, 0, v26, vcc
	s_waitcnt lgkmcnt(0)
	v_add_f32_e32 v79, v0, v27
	v_cndmask_b32_e64 v28, 0, v27, s[38:39]
	v_add_f32_e32 v0, v29, v53
	v_add_f32_e32 v27, v67, v71
	v_add_f32_e32 v0, v0, v27
	ds_bpermute_b32 v29, v65, v0
	s_waitcnt lgkmcnt(0)
	v_add_f32_e32 v0, v0, v29
	ds_bpermute_b32 v32, v69, v0
	v_cndmask_b32_e32 v30, 0, v29, vcc
	v_add_f32_e32 v29, v75, v76
	s_waitcnt lgkmcnt(0)
	v_add_f32_e32 v27, v0, v32
	v_add_f32_e32 v0, v31, v73
	v_add_f32_e32 v0, v0, v29
	ds_bpermute_b32 v29, v65, v0
	v_cndmask_b32_e64 v32, 0, v32, s[38:39]
	s_waitcnt lgkmcnt(0)
	v_add_f32_e32 v0, v0, v29
	ds_bpermute_b32 v45, v69, v0
	v_cndmask_b32_e32 v34, 0, v29, vcc
	v_add_f32_e32 v29, v35, v77
	v_add_f32_e32 v35, v78, v43
	v_add_f32_e32 v29, v29, v35
	s_waitcnt lgkmcnt(0)
	v_add_f32_e32 v31, v0, v45
	v_cndmask_b32_e64 v0, 0, v45, s[38:39]
	ds_bpermute_b32 v45, v65, v29
	s_waitcnt lgkmcnt(0)
	v_add_f32_e32 v29, v29, v45
	ds_bpermute_b32 v80, v69, v29
	s_waitcnt lgkmcnt(0)
	v_add_f32_e32 v35, v29, v80
	v_cndmask_b32_e32 v29, 0, v45, vcc
	v_cndmask_b32_e64 v45, 0, v80, s[38:39]
	v_add_f32_e32 v29, v29, v45
	v_add_f32_e32 v29, 0, v29
	v_add_f32_e32 v41, v41, v29
	v_add_f32_e32 v29, v43, v29
	v_add_f32_e32 v40, v40, v29
	v_add_f32_e32 v29, v78, v29
	v_add_f32_e32 v39, v39, v29
	v_add_f32_e32 v29, v77, v29
	v_pk_add_f32 v[34:35], v[34:35], v[0:1]
	v_add_f32_e32 v29, v38, v29
	v_add_f32_e32 v0, v34, v35
	v_exp_f32_e32 v77, v29
	v_add_f32_e32 v29, v37, v0
	v_add_f32_e32 v0, v76, v0
	v_exp_f32_e32 v81, v29
	v_add_f32_e32 v29, v36, v0
	v_add_f32_e32 v0, v75, v0
	v_exp_f32_e32 v76, v29
	v_add_f32_e32 v29, v74, v0
	v_add_f32_e32 v0, v73, v0
	v_add_f32_e32 v0, v33, v0
	v_mov_b32_e32 v33, v35
	v_pk_add_f32 v[30:31], v[30:31], v[32:33]
	v_exp_f32_e32 v73, v0
	v_add_f32_e32 v0, v30, v31
	v_exp_f32_e32 v74, v29
	v_add_f32_e32 v29, v72, v0
	v_add_f32_e32 v0, v71, v0
	v_exp_f32_e32 v30, v29
	v_add_f32_e32 v29, v70, v0
	v_add_f32_e32 v0, v67, v0
	v_exp_f32_e32 v32, v29
	v_add_f32_e32 v29, v66, v0
	v_exp_f32_e32 v33, v29
	v_add_f32_e32 v0, v53, v0
	v_mov_b32_e32 v29, v31
	v_add_f32_e32 v0, v52, v0
	v_pk_add_f32 v[52:53], v[26:27], v[28:29]
	v_exp_f32_e32 v0, v0
	v_add_f32_e32 v26, v52, v53
	v_add_f32_e32 v27, v51, v26
	v_add_f32_e32 v26, v50, v26
	v_add_f32_e32 v28, v49, v26
	v_exp_f32_e32 v27, v27
	v_exp_f32_e32 v28, v28
	v_add_f32_e32 v26, v48, v26
	v_add_f32_e32 v29, v47, v26
	v_add_f32_e32 v26, v46, v26
	v_add_f32_e32 v26, v44, v26
	v_exp_f32_e32 v29, v29
	v_exp_f32_e32 v26, v26
	v_cvt_pk_bf16_f32 v27, v28, v27
	v_cvt_pk_bf16_f32 v28, v0, v33
	v_lshlrev_b32_e32 v0, 3, v55
	v_mad_u32_u24 v48, v68, s98, v0
	v_add_u32_e32 v71, 0x3000, v48
	v_exp_f32_e32 v80, v41
	v_exp_f32_e32 v43, v40
	v_exp_f32_e32 v78, v39
	v_cvt_pk_bf16_f32 v26, v26, v29
	v_cvt_pk_bf16_f32 v29, v32, v30
	ds_read2_b64 v[38:41], v71 offset0:192 offset1:196
	v_add_u32_e32 v0, 0x2000, v48
	v_add_u32_e32 v70, 0x2800, v48
	v_add_u32_e32 v72, 0x3800, v48
	ds_read2_b64 v[30:33], v0 offset0:128 offset1:132
	ds_read2_b64 v[34:37], v70 offset0:160 offset1:164
	s_waitcnt lgkmcnt(2)
	v_mfma_f32_16x16x32_bf16 v[44:47], v[26:29], v[38:41], 0
	ds_read2_b64 v[38:41], v72 offset0:224 offset1:228
	v_cvt_pk_bf16_f32 v48, v73, v74
	v_cvt_pk_bf16_f32 v49, v76, v81
	s_waitcnt lgkmcnt(2)
	v_mfma_f32_16x16x32_bf16 v[30:33], v[26:29], v[30:33], 0
	v_cvt_pk_bf16_f32 v50, v77, v78
	v_cvt_pk_bf16_f32 v51, v43, v80
	v_add_f32_e32 v67, v79, v53
	s_waitcnt lgkmcnt(1)
	v_mfma_f32_16x16x32_bf16 v[34:37], v[26:29], v[34:37], 0
	v_cmp_gt_f32_e64 s[42:43], s12, v67
	s_waitcnt lgkmcnt(0)
	v_mfma_f32_16x16x32_bf16 v[26:29], v[26:29], v[38:41], 0
	ds_read2_b64 v[38:41], v0 offset0:136 offset1:140
	s_waitcnt lgkmcnt(0)
	v_mfma_f32_16x16x32_bf16 v[38:41], v[48:51], v[38:41], v[30:33]
	s_nop 2
	ds_read2_b64 v[30:33], v70 offset0:168 offset1:172
	s_waitcnt lgkmcnt(0)
	v_mfma_f32_16x16x32_bf16 v[34:37], v[48:51], v[30:33], v[34:37]
	ds_read2_b64 v[30:33], v71 offset0:200 offset1:204
	s_waitcnt lgkmcnt(0)
	v_mfma_f32_16x16x32_bf16 v[30:33], v[48:51], v[30:33], v[44:47]
	s_nop 2
	ds_read2_b64 v[44:47], v72 offset0:232 offset1:236
	s_waitcnt lgkmcnt(0)
	v_mfma_f32_16x16x32_bf16 v[26:29], v[48:51], v[44:47], v[26:29]
	s_and_saveexec_b64 s[80:81], s[40:41]
	s_cbranch_execz .LBB0_192
	s_cmp_eq_u64 s[42:43], s[92:93]
	s_cselect_b64 s[42:43], -1, 0
	v_cndmask_b32_e64 v43, 0, 1, s[42:43]
	v_mov_b64_e32 v[44:45], s[6:7]
	ds_write_b32 v44, v43

.LBB0_192:
	s_or_b64 exec, exec, s[80:81]
	s_mov_b64 s[42:43], src_shared_base
	v_mov_b32_e32 v99, s43
	v_mov_b32_e32 v101, s43
	s_waitcnt lgkmcnt(0)
	s_barrier
	ds_read_b128 v[138:141], v98
	s_waitcnt vmcnt(0)


	v_mov_b32_e32 v103, s43
	v_mov_b32_e32 v105, s43
	s_xor_b64 s[80:81], s[96:97], -1
	s_waitcnt lgkmcnt(0)
	v_and_b32_e32 v43, v138, v139
	v_and_b32_e32 v43, v43, v140


	v_and_b32_e32 v43, v43, v141
	v_cmp_eq_u32_e64 s[42:43], 0, v43
	s_and_b64 s[42:43], s[80:81], s[42:43]
	s_and_saveexec_b64 s[92:93], s[42:43]
	s_cbranch_execz .LBB0_179
	v_mul_u32_u24_e32 v43, 0x90, v68
	s_lshl_b32 s42, s73, 6
	s_add_i32 s66, s42, 0xf40
	s_mov_b64 s[96:97], 0
	v_add_u32_e32 v73, v42, v43
	s_branch .LBB0_195
.LBB0_194:
	s_or_b64 exec, exec, s[82:83]
	s_mov_b64 s[42:43], src_shared_base
	v_mov_b32_e32 v99, s43
	v_mov_b32_e32 v101, s43
	s_waitcnt lgkmcnt(0)
	s_barrier
	ds_read_b128 v[138:141], v98
	s_waitcnt vmcnt(0)


	v_mov_b32_e32 v103, s43
	v_mov_b32_e32 v105, s43
	s_cmp_lt_u32 s72, 2
	s_cselect_b64 s[74:75], -1, 0
	s_sub_i32 s66, s66, 64
	s_add_i32 s72, s72, -1
	s_waitcnt lgkmcnt(0)
	v_and_b32_e32 v42, v138, v139
	v_and_b32_e32 v42, v42, v140


	v_and_b32_e32 v42, v42, v141
	v_cmp_ne_u32_e64 s[42:43], 0, v42
	s_or_b64 s[42:43], s[42:43], s[74:75]
	s_and_b64 s[42:43], exec, s[42:43]
	s_or_b64 s[96:97], s[42:43], s[96:97]
	s_andn2_b64 exec, exec, s[96:97]
	s_cbranch_execz .LBB0_178

.LBB0_197:
	ds_read_b128 v[42:45], v73
	ds_read_b128 v[46:49], v73 offset:64
	ds_read_b128 v[50:53], v73 offset:2304
	ds_read_b128 v[74:77], v73 offset:2368
	s_mov_b64 s[80:81], exec
	s_waitcnt lgkmcnt(3)
	v_mfma_f32_16x16x32_bf16 v[42:45], v[42:45], v[6:9], 0
	s_waitcnt lgkmcnt(1)
	v_mfma_f32_16x16x32_bf16 v[50:53], v[50:53], v[6:9], 0
	v_mfma_f32_16x16x32_bf16 v[46:49], v[46:49], v[10:13], v[42:45]
	s_nop 4
	ds_read_b128 v[42:45], v73 offset:4608
	ds_read_b128 v[78:81], v73 offset:4672
	ds_read_b128 v[82:85], v73 offset:6912
	ds_read_b128 v[86:89], v73 offset:6976
	v_max_f32_e32 v66, v46, v46
	s_waitcnt lgkmcnt(4)
	v_mfma_f32_16x16x32_bf16 v[50:53], v[74:77], v[10:13], v[50:53]
	v_exp_f32_e64 v74, -|v46|
	v_exp_f32_e64 v76, -|v47|
	v_max_f32_e32 v90, 0, v66
	s_waitcnt lgkmcnt(3)
	v_mfma_f32_16x16x32_bf16 v[42:45], v[42:45], v[6:9], 0
	v_add_f32_e32 v66, 1.0, v74
	v_log_f32_e32 v94, v66
	v_add_f32_e32 v66, 1.0, v76
	s_waitcnt lgkmcnt(2)
	v_mfma_f32_16x16x32_bf16 v[42:45], v[78:81], v[10:13], v[42:45]
	v_log_f32_e32 v78, v66
	v_exp_f32_e64 v66, -|v48|
	v_max_f32_e32 v79, v48, v48
	v_max_f32_e32 v91, 0, v79
	v_exp_f32_e64 v79, -|v49|
	v_add_f32_e32 v66, 1.0, v66
	v_exp_f32_e64 v81, -|v50|
	v_log_f32_e32 v95, v66
	v_max_f32_e32 v66, v49, v49
	v_max_f32_e32 v93, 0, v66
	v_add_f32_e32 v66, 1.0, v79
	v_max_f32_e32 v75, v47, v47
	v_log_f32_e32 v79, v66
	v_max_f32_e32 v66, v50, v50
	v_max_f32_e32 v92, 0, v75
	s_waitcnt lgkmcnt(1)
	v_mfma_f32_16x16x32_bf16 v[74:77], v[82:85], v[6:9], 0
	v_max_f32_e32 v80, 0, v66
	v_add_f32_e32 v66, 1.0, v81
	v_exp_f32_e64 v81, -|v51|
	v_exp_f32_e64 v83, -|v52|
	v_log_f32_e32 v82, v66
	v_max_f32_e32 v66, v51, v51
	s_waitcnt lgkmcnt(0)
	v_mfma_f32_16x16x32_bf16 v[74:77], v[86:89], v[10:13], v[74:77]
	v_max_f32_e32 v84, 0, v66
	v_add_f32_e32 v66, 1.0, v81
	v_exp_f32_e64 v87, -|v53|
	v_log_f32_e32 v86, v66
	v_max_f32_e32 v66, v52, v52
	v_max_f32_e32 v81, 0, v66
	v_add_f32_e32 v66, 1.0, v83
	v_exp_f32_e64 v89, -|v42|
	v_log_f32_e32 v83, v66
	v_max_f32_e32 v66, v53, v53
	v_max_f32_e32 v85, 0, v66
	v_add_f32_e32 v66, 1.0, v87
	v_log_f32_e32 v87, v66
	v_max_f32_e32 v66, v42, v42
	v_max_f32_e32 v88, 0, v66
	v_add_f32_e32 v66, 1.0, v89
	v_exp_f32_e64 v89, -|v43|
	v_exp_f32_e64 v97, -|v44|
	v_log_f32_e32 v96, v66
	v_max_f32_e32 v66, v43, v43
	v_max_f32_e32 v106, 0, v66
	v_add_f32_e32 v66, 1.0, v89
	v_exp_f32_e64 v99, -|v45|
	v_log_f32_e32 v108, v66
	v_max_f32_e32 v66, v44, v44
	v_max_f32_e32 v89, 0, v66
	v_add_f32_e32 v66, 1.0, v97
	v_log_f32_e32 v97, v66
	v_max_f32_e32 v66, v45, v45
	v_max_f32_e32 v107, 0, v66
	v_add_f32_e32 v66, 1.0, v99
	v_exp_f32_e64 v99, -|v74|
	v_log_f32_e32 v109, v66
	v_max_f32_e32 v66, v74, v74
	v_max_f32_e32 v110, 0, v66
	v_add_f32_e32 v66, 1.0, v99
	v_exp_f32_e64 v99, -|v75|
	v_log_f32_e32 v112, v66
	v_max_f32_e32 v66, v75, v75
	v_max_f32_e32 v114, 0, v66
	v_add_f32_e32 v66, 1.0, v99
	v_exp_f32_e64 v99, -|v76|
	v_log_f32_e32 v116, v66
	v_max_f32_e32 v66, v76, v76
	v_pk_add_f32 v[80:81], v[80:81], v[82:83]
	v_pk_add_f32 v[82:83], v[84:85], v[86:87]
	v_max_f32_e32 v111, 0, v66
	v_add_f32_e32 v66, 1.0, v99
	v_pk_add_f32 v[84:85], v[82:83], v[80:81] neg_lo:[1,1] neg_hi:[1,1]
	v_log_f32_e32 v113, v66
	v_max_f32_e32 v66, v77, v77
	v_add_f32_e32 v84, v84, v85
	v_max_f32_e32 v115, 0, v66
	v_exp_f32_e64 v66, -|v77|
	ds_bpermute_b32 v87, v65, v84
	v_pk_add_f32 v[90:91], v[90:91], v[94:95]
	v_pk_add_f32 v[78:79], v[92:93], v[78:79]
	v_add_f32_e32 v66, 1.0, v66
	v_log_f32_e32 v117, v66
	s_waitcnt lgkmcnt(0)
	v_add_f32_e32 v66, v84, v87
	v_pk_add_f32 v[92:93], v[78:79], v[90:91] neg_lo:[1,1] neg_hi:[1,1]
	ds_bpermute_b32 v103, v69, v66
	v_add_f32_e32 v92, v92, v93
	ds_bpermute_b32 v93, v65, v92
	v_pk_add_f32 v[88:89], v[88:89], v[96:97]
	v_pk_add_f32 v[94:95], v[106:107], v[108:109]
	s_waitcnt lgkmcnt(1)
	v_add_f32_e32 v85, v66, v103
	v_pk_add_f32 v[96:97], v[94:95], v[88:89] neg_lo:[1,1] neg_hi:[1,1]
	v_pk_add_f32 v[106:107], v[114:115], v[116:117]
	v_add_f32_e32 v66, v96, v97
	v_pk_add_f32 v[96:97], v[110:111], v[112:113]
	s_waitcnt lgkmcnt(0)
	v_add_f32_e32 v99, v92, v93
	v_pk_add_f32 v[108:109], v[106:107], v[96:97] neg_lo:[1,1] neg_hi:[1,1]
	v_cndmask_b32_e32 v84, 0, v93, vcc
	v_add_f32_e32 v93, v108, v109
	v_cndmask_b32_e32 v92, 0, v87, vcc
	ds_bpermute_b32 v87, v65, v66
	ds_bpermute_b32 v105, v65, v93
	v_cndmask_b32_e64 v108, 0, v103, s[38:39]
	v_mov_b32_e32 v113, v107
	v_sub_f32_e32 v45, v45, v95
	s_waitcnt lgkmcnt(1)
	v_add_f32_e32 v66, v66, v87
	s_waitcnt lgkmcnt(0)
	v_add_f32_e32 v103, v93, v105
	ds_bpermute_b32 v109, v69, v66
	ds_bpermute_b32 v112, v69, v103
	ds_bpermute_b32 v101, v69, v99
	v_sub_f32_e32 v53, v53, v83
	v_sub_f32_e32 v49, v49, v79
	s_waitcnt lgkmcnt(2)
	v_add_f32_e32 v93, v66, v109
	v_cndmask_b32_e32 v66, 0, v87, vcc
	v_sub_f32_e32 v87, v77, v107
	s_waitcnt lgkmcnt(1)
	v_add_f32_e32 v111, v103, v112
	v_cndmask_b32_e32 v77, 0, v105, vcc
	v_cndmask_b32_e64 v103, 0, v112, s[38:39]
	v_add_f32_e32 v77, v77, v103
	v_add_f32_e32 v77, v67, v77
	v_mov_b32_e32 v112, v97
	v_add_f32_e32 v87, v87, v77
	v_pk_add_f32 v[76:77], v[76:77], v[112:113] neg_lo:[0,1] neg_hi:[0,1]
	v_mov_b32_e32 v107, v97
	v_add_f32_e32 v76, v76, v77
	v_exp_f32_e32 v105, v76
	v_mov_b32_e32 v76, v75
	v_pk_add_f32 v[76:77], v[76:77], v[106:107] neg_lo:[0,1] neg_hi:[0,1]
	v_cndmask_b32_e64 v110, 0, v109, s[38:39]
	v_add_f32_e32 v75, v76, v77
	v_exp_f32_e32 v107, v75
	v_mov_b32_e32 v75, v77
	v_mov_b32_e32 v97, v106
	v_pk_add_f32 v[74:75], v[74:75], v[96:97] neg_lo:[0,1] neg_hi:[0,1]
	v_pk_add_f32 v[66:67], v[66:67], v[110:111]
	v_add_f32_e32 v96, v74, v75
	v_pk_add_f32 v[74:75], v[66:67], v[66:67] op_sel:[0,1] op_sel_hi:[1,0]
	v_mov_b32_e32 v109, v67
	v_add_f32_e32 v45, v45, v74
	v_exp_f32_e32 v97, v45
	v_mov_b32_e32 v45, v74
	v_mov_b32_e32 v74, v89
	v_mov_b32_e32 v75, v95
	v_pk_add_f32 v[74:75], v[44:45], v[74:75] neg_lo:[0,1] neg_hi:[0,1]
	v_pk_add_f32 v[44:45], v[92:93], v[108:109]
	v_add_f32_e32 v106, v74, v75
	v_pk_add_f32 v[66:67], v[44:45], v[44:45] op_sel:[0,1] op_sel_hi:[1,0]
	v_mov_b32_e32 v74, v43
	v_add_f32_e32 v43, v53, v66
	v_mov_b32_e32 v53, v66
	v_mov_b32_e32 v66, v81
	v_mov_b32_e32 v67, v83
	v_pk_add_f32 v[52:53], v[52:53], v[66:67] neg_lo:[0,1] neg_hi:[0,1]
	v_mov_b32_e32 v83, v81
	v_add_f32_e32 v66, v52, v53
	v_mov_b32_e32 v52, v51
	s_waitcnt lgkmcnt(0)
	v_cndmask_b32_e64 v86, 0, v101, s[38:39]
	v_exp_f32_e32 v103, v87
	v_pk_add_f32 v[52:53], v[52:53], v[82:83] neg_lo:[0,1] neg_hi:[0,1]
	v_mov_b32_e32 v87, v45
	v_add_f32_e32 v44, v52, v53
	v_mov_b32_e32 v51, v53
	v_pk_add_f32 v[52:53], v[84:85], v[86:87]
	v_exp_f32_e32 v67, v44
	v_mov_b32_e32 v81, v82
	v_pk_add_f32 v[44:45], v[52:53], v[52:53] op_sel:[0,1] op_sel_hi:[1,0]
	v_pk_add_f32 v[50:51], v[50:51], v[80:81] neg_lo:[0,1] neg_hi:[0,1]
	v_add_f32_e32 v45, v49, v44
	v_add_f32_e32 v50, v50, v51
	v_exp_f32_e32 v51, v45
	v_mov_b32_e32 v49, v44
	v_mov_b32_e32 v44, v91
	v_mov_b32_e32 v45, v79
	v_pk_add_f32 v[44:45], v[48:49], v[44:45] neg_lo:[0,1] neg_hi:[0,1]
	v_mov_b32_e32 v79, v91
	v_add_f32_e32 v48, v44, v45
	v_mov_b32_e32 v44, v47
	v_pk_add_f32 v[44:45], v[44:45], v[78:79] neg_lo:[0,1] neg_hi:[0,1]
	v_mov_b32_e32 v91, v78
	v_add_f32_e32 v44, v44, v45
	v_mov_b32_e32 v47, v45
	v_exp_f32_e32 v49, v44
	v_pk_add_f32 v[44:45], v[46:47], v[90:91] neg_lo:[0,1] neg_hi:[0,1]
	v_exp_f32_e32 v43, v43
	v_add_f32_e32 v44, v44, v45
	v_exp_f32_e32 v44, v44
	v_exp_f32_e32 v45, v48
	v_exp_f32_e32 v46, v50
	v_exp_f32_e32 v47, v66
	v_cvt_pk_bf16_f32 v44, v44, v49
	v_cvt_pk_bf16_f32 v45, v45, v51
	v_cvt_pk_bf16_f32 v46, v46, v67
	v_cvt_pk_bf16_f32 v47, v47, v43
	ds_read2_b64 v[48:51], v0 offset0:128 offset1:132
	v_mov_b32_e32 v95, v89
	v_pk_add_f32 v[66:67], v[74:75], v[94:95] neg_lo:[0,1] neg_hi:[0,1]
	ds_read2_b64 v[74:77], v70 offset0:160 offset1:164
	s_waitcnt lgkmcnt(1)
	v_mfma_f32_16x16x32_bf16 v[38:41], v[44:47], v[48:51], v[38:41]
	ds_read2_b64 v[48:51], v71 offset0:192 offset1:196
	v_add_f32_e32 v43, v66, v67
	v_exp_f32_e32 v52, v43
	v_mov_b32_e32 v43, v67
	v_mov_b32_e32 v89, v94
	v_pk_add_f32 v[42:43], v[42:43], v[88:89] neg_lo:[0,1] neg_hi:[0,1]
	s_waitcnt lgkmcnt(1)
	v_mfma_f32_16x16x32_bf16 v[34:37], v[44:47], v[74:77], v[34:37]
	v_add_f32_e32 v42, v42, v43
	ds_read2_b64 v[74:77], v72 offset0:224 offset1:228
	v_exp_f32_e32 v42, v42
	s_waitcnt lgkmcnt(1)
	v_mfma_f32_16x16x32_bf16 v[30:33], v[44:47], v[48:51], v[30:33]
	v_exp_f32_e32 v43, v106
	v_exp_f32_e32 v48, v96
	v_cvt_pk_bf16_f32 v42, v42, v52
	s_waitcnt lgkmcnt(0)
	v_mfma_f32_16x16x32_bf16 v[26:29], v[44:47], v[74:77], v[26:29]
	v_cvt_pk_bf16_f32 v43, v43, v97
	v_cvt_pk_bf16_f32 v44, v48, v107
	v_cvt_pk_bf16_f32 v45, v105, v103
	ds_read2_b64 v[46:49], v0 offset0:136 offset1:140
	v_add_f32_e32 v50, v99, v101
	ds_read2_b64 v[142:145], v70 offset0:168 offset1:172
	ds_read2_b64 v[146:149], v71 offset0:200 offset1:204
	ds_read2_b64 v[150:153], v72 offset0:232 offset1:236
	v_add_f32_e32 v67, v50, v53
	v_cmp_gt_f32_e64 s[42:43], s12, v67
	s_waitcnt lgkmcnt(3)
	v_mfma_f32_16x16x32_bf16 v[38:41], v[42:45], v[46:49], v[38:41]
	s_waitcnt lgkmcnt(2)
	v_mfma_f32_16x16x32_bf16 v[34:37], v[42:45], v[142:145], v[34:37]
	s_waitcnt lgkmcnt(1)
	v_mfma_f32_16x16x32_bf16 v[30:33], v[42:45], v[146:149], v[30:33]
	s_waitcnt lgkmcnt(0)
	v_mfma_f32_16x16x32_bf16 v[26:29], v[42:45], v[150:153], v[26:29]
	s_and_saveexec_b64 s[82:83], s[40:41]
	s_cbranch_execz .LBB0_194
	s_cmp_eq_u64 s[42:43], s[80:81]
	s_cselect_b64 s[42:43], -1, 0
	v_cndmask_b32_e64 v44, 0, 1, s[42:43]
	v_mov_b64_e32 v[42:43], s[6:7]
	ds_write_b32 v42, v44

	s_branch .LBB0_194

.LBB0_304:
	s_andn2_b64 vcc, exec, s[6:7]
	s_cbranch_vccnz .LBB0_397
	s_cmp_gt_i32 s19, 0
	s_mov_b64 s[6:7], -1
	s_cbranch_scc0 .LBB0_325
	s_lshl_b32 s6, s71, 2
	s_abs_i32 s7, s6
	v_cvt_f32_u32_e32 v0, s7
	s_sub_i32 s21, 0, s7
	s_add_i32 s20, s6, 0x3fff
	s_xor_b32 s6, s20, s6
	v_rcp_iflag_f32_e32 v0, v0
	s_abs_i32 s20, s20
	s_waitcnt vmcnt(0)
	v_mov_b32_e32 v18, v154
	v_mov_b32_e32 v2, v154
	v_mul_f32_e32 v0, 0x4f7ffffe, v0
	v_cvt_u32_f32_e32 v0, v0
	s_ashr_i32 s6, s6, 31
	v_readfirstlane_b32 s22, v0
	s_mul_i32 s21, s21, s22
	s_mul_hi_u32 s21, s22, s21
	s_add_i32 s22, s22, s21
	s_mul_hi_u32 s21, s20, s22
	s_mul_i32 s22, s21, s7
	v_readfirstlane_b32 s18, v2
	s_sub_i32 s20, s20, s22
	s_ashr_i32 s18, s18, 6
	s_add_i32 s22, s21, 1
	s_sub_i32 s23, s20, s7
	s_cmp_ge_u32 s20, s7
	s_cselect_b32 s21, s22, s21
	s_cselect_b32 s20, s23, s20
	s_add_i32 s22, s21, 1
	s_cmp_ge_u32 s20, s7
	s_cselect_b32 s7, s22, s21
	s_xor_b32 s7, s7, s6
	s_sub_i32 s7, s7, s6
	s_lshl_b32 s6, s3, 2
	s_add_i32 s6, s18, s6
	s_mul_i32 s6, s6, s7
	s_cmpk_gt_i32 s6, 0x3fff
	s_cbranch_scc1 .LBB0_324
	s_waitcnt lgkmcnt(0)
	s_load_dwordx2 s[24:25], s[0:1], 0xc0
	s_load_dwordx2 s[28:29], s[0:1], 0x20
	s_ashr_i32 s18, s6, 12
	s_load_dwordx2 s[26:27], s[0:1], 0xb8
	s_mul_i32 s20, s18, 0x1800
	s_waitcnt lgkmcnt(0)
	s_cmp_eq_u64 s[24:25], 0
	s_cselect_b64 s[22:23], -1, 0
	s_cmp_lg_u64 s[24:25], 0
	s_cselect_b64 s[34:35], -1, 0
	s_ashr_i32 s21, s20, 31
	s_lshl_b64 s[20:21], s[20:21], 2
	s_add_u32 s26, s26, s20
	v_lshlrev_b32_e32 v0, 2, v18
	s_addc_u32 s27, s27, s21
	v_and_b32_e32 v0, 0xfc, v0
	s_add_u32 s30, s26, 0x1000
	s_addc_u32 s31, s27, 0
	s_and_b64 vcc, exec, s[34:35]
	v_lshlrev_b32_e32 v0, 2, v0
	s_cbranch_vccz .LBB0_309
	global_load_dwordx4 v[188:191], v0, s[30:31]
	s_add_u32 s54, s30, 0x30000
	s_addc_u32 s55, s31, 0
	global_load_dwordx4 v[192:195], v0, s[54:55]
	s_mov_b32 s18, 0x60000
	global_load_dwordx4 v[2:5], v0, s[28:29]
	s_add_u32 s56, s30, 0x60000
	s_addc_u32 s57, s31, 0
	global_load_dwordx4 v[196:199], v0, s[56:57]
	s_add_u32 s62, s30, 0x90000
	s_addc_u32 s63, s31, 0
	global_load_dwordx4 v[200:203], v0, s[62:63]
	global_load_dwordx4 v[204:207], v0, s[26:27]
	s_add_u32 s54, s26, 0x30000
	s_addc_u32 s55, s27, 0
	global_load_dwordx4 v[208:211], v0, s[54:55]
	s_add_u32 s56, s26, 0x60000
	s_addc_u32 s57, s27, 0
	global_load_dwordx4 v[212:215], v0, s[56:57]
	s_mov_b32 s18, 0x90000
	s_add_u32 s62, s26, 0x90000
	s_addc_u32 s63, s27, 0
	global_load_dwordx4 v[216:219], v0, s[62:63]
	s_waitcnt vmcnt(0)
	v_pk_add_f32 v[52:53], v[190:191], v[194:195]
	v_pk_add_f32 v[52:53], v[52:53], v[198:199]
	v_pk_add_f32 v[52:53], v[52:53], v[202:203]
	v_pk_add_f32 v[52:53], v[52:53], 1.0 op_sel_hi:[1,0]
	v_pk_add_f32 v[50:51], v[188:189], v[192:193]
	v_pk_add_f32 v[50:51], v[50:51], v[196:197]
	v_pk_add_f32 v[50:51], v[50:51], v[200:201]
	v_pk_add_f32 v[50:51], v[50:51], 1.0 op_sel_hi:[1,0]
	v_pk_add_f32 v[56:57], v[206:207], v[210:211]
	v_pk_add_f32 v[56:57], v[56:57], v[214:215]
	v_pk_add_f32 v[56:57], v[56:57], v[218:219]
	v_pk_add_f32 v[54:55], v[204:205], v[208:209]
	v_pk_add_f32 v[54:55], v[54:55], v[212:213]
	v_pk_add_f32 v[54:55], v[54:55], v[216:217]
.LBB0_309:
	v_cndmask_b32_e64 v6, 0, 1, s[34:35]
	v_cmp_ne_u32_e64 s[38:39], 1, v6
	s_andn2_b64 vcc, exec, s[34:35]
	s_cbranch_vccnz .LBB0_311
	global_load_dwordx4 v[188:191], v0, s[30:31] offset:1024
	s_add_u32 s54, s30, 0x30000
	s_addc_u32 s55, s31, 0
	global_load_dwordx4 v[192:195], v0, s[54:55] offset:1024
	s_mov_b32 s18, 0x60000
	global_load_dwordx4 v[6:9], v0, s[28:29] offset:1024
	s_add_u32 s56, s30, 0x60000
	s_addc_u32 s57, s31, 0
	global_load_dwordx4 v[196:199], v0, s[56:57] offset:1024
	s_add_u32 s62, s30, 0x90000
	s_addc_u32 s63, s31, 0
	global_load_dwordx4 v[200:203], v0, s[62:63] offset:1024
	global_load_dwordx4 v[204:207], v0, s[26:27] offset:1024
	s_add_u32 s54, s26, 0x30000
	s_addc_u32 s55, s27, 0
	global_load_dwordx4 v[208:211], v0, s[54:55] offset:1024
	s_add_u32 s56, s26, 0x60000
	s_addc_u32 s57, s27, 0
	global_load_dwordx4 v[212:215], v0, s[56:57] offset:1024
	s_mov_b32 s18, 0x90000
	s_add_u32 s62, s26, 0x90000
	s_addc_u32 s63, s27, 0
	global_load_dwordx4 v[216:219], v0, s[62:63] offset:1024
	s_waitcnt vmcnt(0)
	v_pk_add_f32 v[60:61], v[190:191], v[194:195]
	v_pk_add_f32 v[60:61], v[60:61], v[198:199]
	v_pk_add_f32 v[60:61], v[60:61], v[202:203]
	v_pk_add_f32 v[60:61], v[60:61], 1.0 op_sel_hi:[1,0]
	v_pk_add_f32 v[58:59], v[188:189], v[192:193]
	v_pk_add_f32 v[58:59], v[58:59], v[196:197]
	v_pk_add_f32 v[58:59], v[58:59], v[200:201]
	v_pk_add_f32 v[58:59], v[58:59], 1.0 op_sel_hi:[1,0]
	v_pk_add_f32 v[64:65], v[206:207], v[210:211]
	v_pk_add_f32 v[64:65], v[64:65], v[214:215]
	v_pk_add_f32 v[64:65], v[64:65], v[218:219]
	v_pk_add_f32 v[62:63], v[204:205], v[208:209]
	v_pk_add_f32 v[62:63], v[62:63], v[212:213]
	v_pk_add_f32 v[62:63], v[62:63], v[216:217]
.LBB0_311:
	s_and_b64 vcc, exec, s[38:39]
	s_cbranch_vccnz .LBB0_313
	global_load_dwordx4 v[188:191], v0, s[30:31] offset:2048
	s_add_u32 s54, s30, 0x30000
	s_addc_u32 s55, s31, 0
	global_load_dwordx4 v[192:195], v0, s[54:55] offset:2048
	s_mov_b32 s18, 0x60000
	global_load_dwordx4 v[10:13], v0, s[28:29] offset:2048
	s_add_u32 s56, s30, 0x60000
	s_addc_u32 s57, s31, 0
	global_load_dwordx4 v[196:199], v0, s[56:57] offset:2048
	s_add_u32 s62, s30, 0x90000
	s_addc_u32 s63, s31, 0
	global_load_dwordx4 v[200:203], v0, s[62:63] offset:2048
	global_load_dwordx4 v[204:207], v0, s[26:27] offset:2048
	s_add_u32 s54, s26, 0x30000
	s_addc_u32 s55, s27, 0
	global_load_dwordx4 v[208:211], v0, s[54:55] offset:2048
	s_add_u32 s56, s26, 0x60000
	s_addc_u32 s57, s27, 0
	global_load_dwordx4 v[212:215], v0, s[56:57] offset:2048
	s_mov_b32 s18, 0x90000
	s_add_u32 s62, s26, 0x90000
	s_addc_u32 s63, s27, 0
	global_load_dwordx4 v[216:219], v0, s[62:63] offset:2048
	s_waitcnt vmcnt(0)
	v_pk_add_f32 v[68:69], v[190:191], v[194:195]
	v_pk_add_f32 v[68:69], v[68:69], v[198:199]
	v_pk_add_f32 v[68:69], v[68:69], v[202:203]
	v_pk_add_f32 v[68:69], v[68:69], 1.0 op_sel_hi:[1,0]
	v_pk_add_f32 v[66:67], v[188:189], v[192:193]
	v_pk_add_f32 v[66:67], v[66:67], v[196:197]
	v_pk_add_f32 v[66:67], v[66:67], v[200:201]
	v_pk_add_f32 v[66:67], v[66:67], 1.0 op_sel_hi:[1,0]
	v_pk_add_f32 v[72:73], v[206:207], v[210:211]
	v_pk_add_f32 v[72:73], v[72:73], v[214:215]
	v_pk_add_f32 v[72:73], v[72:73], v[218:219]
	v_pk_add_f32 v[70:71], v[204:205], v[208:209]
	v_pk_add_f32 v[70:71], v[70:71], v[212:213]
	v_pk_add_f32 v[70:71], v[70:71], v[216:217]
.LBB0_313:
	s_and_b64 vcc, exec, s[38:39]
	s_cbranch_vccnz .LBB0_315
	global_load_dwordx4 v[188:191], v0, s[30:31] offset:3072
	s_add_u32 s54, s30, 0x30000
	s_addc_u32 s55, s31, 0
	global_load_dwordx4 v[192:195], v0, s[54:55] offset:3072
	s_mov_b32 s18, 0x60000
	global_load_dwordx4 v[14:17], v0, s[28:29] offset:3072
	s_add_u32 s56, s30, 0x60000
	s_addc_u32 s57, s31, 0
	global_load_dwordx4 v[196:199], v0, s[56:57] offset:3072
	s_add_u32 s62, s30, 0x90000
	s_addc_u32 s63, s31, 0
	global_load_dwordx4 v[200:203], v0, s[62:63] offset:3072
	global_load_dwordx4 v[204:207], v0, s[26:27] offset:3072
	s_add_u32 s54, s26, 0x30000
	s_addc_u32 s55, s27, 0
	global_load_dwordx4 v[208:211], v0, s[54:55] offset:3072
	s_add_u32 s56, s26, 0x60000
	s_addc_u32 s57, s27, 0
	global_load_dwordx4 v[212:215], v0, s[56:57] offset:3072
	s_mov_b32 s18, 0x90000
	s_add_u32 s62, s26, 0x90000
	s_addc_u32 s63, s27, 0
	global_load_dwordx4 v[216:219], v0, s[62:63] offset:3072
	s_add_i32 s7, s6, s7
	s_min_i32 s18, s7, 0x4000
	s_cmp_lt_i32 s6, s18
	s_waitcnt vmcnt(0)
	v_pk_add_f32 v[76:77], v[190:191], v[194:195]
	v_pk_add_f32 v[76:77], v[76:77], v[198:199]
	v_pk_add_f32 v[76:77], v[76:77], v[202:203]
	v_pk_add_f32 v[76:77], v[76:77], 1.0 op_sel_hi:[1,0]
	v_pk_add_f32 v[74:75], v[188:189], v[192:193]
	v_pk_add_f32 v[74:75], v[74:75], v[196:197]
	v_pk_add_f32 v[74:75], v[74:75], v[200:201]
	v_pk_add_f32 v[74:75], v[74:75], 1.0 op_sel_hi:[1,0]
	v_pk_add_f32 v[80:81], v[206:207], v[210:211]
	v_pk_add_f32 v[80:81], v[80:81], v[214:215]
	v_pk_add_f32 v[80:81], v[80:81], v[218:219]
	v_pk_add_f32 v[78:79], v[204:205], v[208:209]
	v_pk_add_f32 v[78:79], v[78:79], v[212:213]
	v_pk_add_f32 v[78:79], v[78:79], v[216:217]
	s_cbranch_scc0 .LBB0_324
	s_branch .LBB0_316

.LBB0_322:
	s_waitcnt vmcnt(3)
	v_mov_b32_e32 v86, v47
	s_waitcnt vmcnt(2)
	v_mov_b32_e32 v87, v43
	v_mov_b32_e32 v84, v46
	v_mov_b32_e32 v85, v42
	v_pk_mul_f32 v[86:87], v[86:87], v[86:87]
	s_waitcnt vmcnt(1)
	v_mov_b32_e32 v88, v39
	v_pk_fma_f32 v[84:85], v[84:85], v[84:85], v[86:87]
	v_mov_b32_e32 v86, v48
	v_mov_b32_e32 v87, v44
	v_pk_fma_f32 v[84:85], v[86:87], v[86:87], v[84:85]
	v_mov_b32_e32 v86, v49
	v_mov_b32_e32 v87, v45
	s_waitcnt vmcnt(0)
	v_mov_b32_e32 v89, v35
	v_pk_fma_f32 v[84:85], v[86:87], v[86:87], v[84:85]
	v_mov_b32_e32 v86, v38
	v_mov_b32_e32 v87, v34
	v_pk_mul_f32 v[88:89], v[88:89], v[88:89]
	v_add_f32_e32 v84, v84, v85
	v_pk_fma_f32 v[86:87], v[86:87], v[86:87], v[88:89]
	v_mov_b32_e32 v88, v40
	v_mov_b32_e32 v89, v36
	v_pk_fma_f32 v[86:87], v[88:89], v[88:89], v[86:87]
	v_mov_b32_e32 v88, v41
	v_mov_b32_e32 v89, v37
	v_pk_fma_f32 v[86:87], v[88:89], v[88:89], v[86:87]
	v_add_f32_e32 v84, v84, v86
	v_add_f32_e32 v84, v84, v87
	s_nop 0
	s_nop 1
	v_add_f32_dpp v84, v84, v84 row_shr:1 row_mask:0xf bank_mask:0xf
	s_nop 1
	v_add_f32_dpp v84, v84, v84 row_shr:2 row_mask:0xf bank_mask:0xf
	s_nop 1
	v_add_f32_dpp v84, v84, v84 row_shr:4 row_mask:0xf bank_mask:0xf
	s_nop 1
	v_add_f32_dpp v84, v84, v84 row_shr:8 row_mask:0xf bank_mask:0xf
	s_nop 1
	v_readlane_b32 s54, v84, 15
	v_readlane_b32 s55, v84, 31
	v_readlane_b32 s56, v84, 47
	v_readlane_b32 s57, v84, 63
	s_nop 3
	v_mov_b32_e32 v84, s54
	v_add_f32_e32 v84, s55, v84
	v_add_f32_e32 v84, s56, v84
	v_add_f32_e32 v84, s57, v84
	v_lshl_add_u64 v[86:87], s[24:25], 0, v[82:83]
	v_fmamk_f32 v84, v84, 0x3a800000, v155
	v_mul_f32_e32 v85, 0x4b800000, v84
	v_cmp_gt_f32_e32 vcc, s84, v84
	s_nop 1
	v_cndmask_b32_e32 v84, v84, v85, vcc
	v_rsq_f32_e32 v84, v84
	s_nop 0
	v_mul_f32_e32 v85, 0x45800000, v84
	v_cndmask_b32_e32 v84, v84, v85, vcc
	v_pk_mul_f32 v[48:49], v[48:49], v[84:85] op_sel_hi:[1,0]
	v_pk_mul_f32 v[46:47], v[46:47], v[84:85] op_sel_hi:[1,0]
	v_pk_mul_f32 v[44:45], v[44:45], v[84:85] op_sel_hi:[1,0]
	v_pk_mul_f32 v[42:43], v[42:43], v[84:85] op_sel_hi:[1,0]
	v_pk_mul_f32 v[40:41], v[40:41], v[84:85] op_sel_hi:[1,0]
	v_pk_mul_f32 v[38:39], v[38:39], v[84:85] op_sel_hi:[1,0]
	v_pk_mul_f32 v[36:37], v[36:37], v[84:85] op_sel_hi:[1,0]
	v_pk_mul_f32 v[34:35], v[34:35], v[84:85] op_sel_hi:[1,0]
	v_pk_mul_f32 v[46:47], v[2:3], v[46:47]
	v_pk_mul_f32 v[48:49], v[4:5], v[48:49]
	v_pk_mul_f32 v[42:43], v[6:7], v[42:43]
	v_pk_mul_f32 v[44:45], v[8:9], v[44:45]
	v_pk_mul_f32 v[38:39], v[10:11], v[38:39]
	v_pk_mul_f32 v[40:41], v[12:13], v[40:41]
	v_pk_mul_f32 v[34:35], v[14:15], v[34:35]
	v_pk_mul_f32 v[36:37], v[16:17], v[36:37]
	v_pk_fma_f32 v[48:49], v[52:53], v[48:49], v[56:57]
	v_pk_fma_f32 v[46:47], v[50:51], v[46:47], v[54:55]
	v_pk_fma_f32 v[44:45], v[60:61], v[44:45], v[64:65]
	v_pk_fma_f32 v[42:43], v[58:59], v[42:43], v[62:63]
	v_pk_fma_f32 v[40:41], v[68:69], v[40:41], v[72:73]
	v_pk_fma_f32 v[38:39], v[66:67], v[38:39], v[70:71]
	v_pk_fma_f32 v[36:37], v[76:77], v[36:37], v[80:81]
	v_pk_fma_f32 v[34:35], v[74:75], v[34:35], v[78:79]
	v_cvt_pk_bf16_f32 v46, v46, v47
	v_cvt_pk_bf16_f32 v47, v48, v49
	v_cvt_pk_bf16_f32 v42, v42, v43
	v_cvt_pk_bf16_f32 v43, v44, v45
	v_cvt_pk_bf16_f32 v38, v38, v39
	v_cvt_pk_bf16_f32 v39, v40, v41
	v_cvt_pk_bf16_f32 v34, v34, v35
	v_cvt_pk_bf16_f32 v35, v36, v37
	v_readlane_b32 vcc_lo, v244, 60
	v_readlane_b32 vcc_hi, v244, 61
	s_nop 3
	v_subrev_u32_e32 v48, vcc_lo, v86
	v_and_b32_e32 v44, 0x7ff, v48
	v_lshrrev_b32_e32 v48, 11, v48
	v_lshlrev_b32_e32 v48, 6, v48
	v_lshrrev_b32_e32 v45, 6, v44
	v_lshl_or_b32 v48, v45, 20, v48
	v_and_or_b32 v48, v44, 63, v48
	v_mov_b32_e32 v49, 0
	v_lshl_add_u64 v[48:49], vcc, 0, v[48:49]
	global_store_dwordx2 v[48:49], v[46:47], off
	v_subrev_u32_e32 v48, vcc_lo, v86
	v_add_u32_e32 v48, 0x200, v48
	v_and_b32_e32 v44, 0x7ff, v48
	v_lshrrev_b32_e32 v48, 11, v48
	v_lshlrev_b32_e32 v48, 6, v48
	v_lshrrev_b32_e32 v45, 6, v44
	v_lshl_or_b32 v48, v45, 20, v48
	v_and_or_b32 v48, v44, 63, v48
	v_mov_b32_e32 v49, 0
	v_lshl_add_u64 v[48:49], vcc, 0, v[48:49]
	global_store_dwordx2 v[48:49], v[42:43], off
	v_subrev_u32_e32 v48, vcc_lo, v86
	v_add_u32_e32 v48, 0x400, v48
	v_and_b32_e32 v44, 0x7ff, v48
	v_lshrrev_b32_e32 v48, 11, v48
	v_lshlrev_b32_e32 v48, 6, v48
	v_lshrrev_b32_e32 v45, 6, v44
	v_lshl_or_b32 v48, v45, 20, v48
	v_and_or_b32 v48, v44, 63, v48
	v_mov_b32_e32 v49, 0
	v_lshl_add_u64 v[48:49], vcc, 0, v[48:49]
	global_store_dwordx2 v[48:49], v[38:39], off
	v_subrev_u32_e32 v48, vcc_lo, v86
	v_add_u32_e32 v48, 0x600, v48
	v_and_b32_e32 v44, 0x7ff, v48
	v_lshrrev_b32_e32 v48, 11, v48
	v_lshlrev_b32_e32 v48, 6, v48
	v_lshrrev_b32_e32 v45, 6, v44
	v_lshl_or_b32 v48, v45, 20, v48
	v_and_or_b32 v48, v44, 63, v48
	v_mov_b32_e32 v49, 0
	v_lshl_add_u64 v[48:49], vcc, 0, v[48:49]
	global_store_dwordx2 v[48:49], v[34:35], off
	s_or_b64 s[20:21], s[22:23], s[34:35]
	s_and_b64 vcc, exec, s[20:21]
	s_cbranch_vccnz .LBB0_317
.LBB0_323:
	s_nop 1
	v_mov_b32_e32 v36, v27
	v_mov_b32_e32 v37, v31
	v_mov_b32_e32 v34, v26
	v_mov_b32_e32 v35, v30
	v_pk_mul_f32 v[36:37], v[36:37], v[36:37]
	v_mov_b32_e32 v38, v19
	v_pk_fma_f32 v[34:35], v[34:35], v[34:35], v[36:37]
	v_mov_b32_e32 v36, v28
	v_mov_b32_e32 v37, v32
	v_pk_fma_f32 v[34:35], v[36:37], v[36:37], v[34:35]
	v_mov_b32_e32 v36, v29
	v_mov_b32_e32 v37, v33
	v_mov_b32_e32 v39, v23
	v_pk_fma_f32 v[34:35], v[36:37], v[36:37], v[34:35]
	v_mov_b32_e32 v36, v18
	v_mov_b32_e32 v37, v22
	v_pk_mul_f32 v[38:39], v[38:39], v[38:39]
	v_add_f32_e32 v34, v34, v35
	v_pk_fma_f32 v[36:37], v[36:37], v[36:37], v[38:39]
	v_mov_b32_e32 v38, v20
	v_mov_b32_e32 v39, v24
	v_pk_fma_f32 v[36:37], v[38:39], v[38:39], v[36:37]
	v_mov_b32_e32 v38, v21
	v_mov_b32_e32 v39, v25
	v_pk_fma_f32 v[36:37], v[38:39], v[38:39], v[36:37]
	v_add_f32_e32 v34, v37, v34
	v_add_f32_e32 v34, v36, v34
	s_nop 1
	v_add_f32_dpp v34, v34, v34 row_shr:1 row_mask:0xf bank_mask:0xf
	s_nop 1
	v_add_f32_dpp v34, v34, v34 row_shr:2 row_mask:0xf bank_mask:0xf
	s_nop 1
	v_add_f32_dpp v34, v34, v34 row_shr:4 row_mask:0xf bank_mask:0xf
	s_nop 1
	v_add_f32_dpp v34, v34, v34 row_shr:8 row_mask:0xf bank_mask:0xf
	s_nop 1
	v_readlane_b32 s54, v34, 15
	v_readlane_b32 s55, v34, 31
	v_readlane_b32 s56, v34, 47
	v_readlane_b32 s57, v34, 63
	s_nop 3
	v_mov_b32_e32 v34, s54
	v_add_f32_e32 v34, s55, v34
	v_add_f32_e32 v34, s56, v34
	v_add_f32_e32 v34, s57, v34
	v_lshl_add_u64 v[36:37], s[28:29], 0, v[82:83]
	v_fmamk_f32 v34, v34, 0x3a800000, v155
	v_mul_f32_e32 v35, 0x4b800000, v34
	v_cmp_gt_f32_e32 vcc, s84, v34
	s_nop 1
	v_cndmask_b32_e32 v34, v34, v35, vcc
	v_rsq_f32_e32 v34, v34
	s_nop 0
	v_mul_f32_e32 v35, 0x45800000, v34
	v_cndmask_b32_e32 v34, v34, v35, vcc
	v_pk_mul_f32 v[38:39], v[32:33], v[34:35] op_sel_hi:[1,0]
	v_pk_mul_f32 v[40:41], v[30:31], v[34:35] op_sel_hi:[1,0]
	v_pk_mul_f32 v[38:39], v[4:5], v[38:39]
	v_pk_mul_f32 v[40:41], v[2:3], v[40:41]
	v_pk_fma_f32 v[38:39], v[52:53], v[38:39], v[56:57]
	v_pk_fma_f32 v[40:41], v[50:51], v[40:41], v[54:55]
	s_nop 0
	v_cvt_pk_bf16_f32 v40, v40, v41
	v_cvt_pk_bf16_f32 v41, v38, v39
	v_readlane_b32 vcc_lo, v244, 60
	v_readlane_b32 vcc_hi, v244, 61
	s_nop 3
	v_subrev_u32_e32 v30, vcc_lo, v36
	v_and_b32_e32 v32, 0x7ff, v30
	v_lshrrev_b32_e32 v30, 11, v30
	v_lshlrev_b32_e32 v30, 6, v30
	v_lshrrev_b32_e32 v33, 6, v32
	v_lshl_or_b32 v30, v33, 20, v30
	v_and_or_b32 v30, v32, 63, v30
	v_mov_b32_e32 v31, 0
	v_lshl_add_u64 v[30:31], vcc, 0, v[30:31]
	global_store_dwordx2 v[30:31], v[40:41], off
	v_pk_mul_f32 v[38:39], v[28:29], v[34:35] op_sel_hi:[1,0]
	v_pk_mul_f32 v[40:41], v[26:27], v[34:35] op_sel_hi:[1,0]
	v_pk_mul_f32 v[38:39], v[8:9], v[38:39]
	v_pk_mul_f32 v[40:41], v[6:7], v[40:41]
	v_pk_fma_f32 v[38:39], v[60:61], v[38:39], v[64:65]
	v_pk_fma_f32 v[40:41], v[58:59], v[40:41], v[62:63]
	s_nop 0
	v_cvt_pk_bf16_f32 v40, v40, v41
	v_cvt_pk_bf16_f32 v41, v38, v39
	v_subrev_u32_e32 v30, vcc_lo, v36
	v_add_u32_e32 v30, 0x200, v30
	v_and_b32_e32 v32, 0x7ff, v30
	v_lshrrev_b32_e32 v30, 11, v30
	v_lshlrev_b32_e32 v30, 6, v30
	v_lshrrev_b32_e32 v33, 6, v32
	v_lshl_or_b32 v30, v33, 20, v30
	v_and_or_b32 v30, v32, 63, v30
	v_mov_b32_e32 v31, 0
	v_lshl_add_u64 v[30:31], vcc, 0, v[30:31]
	global_store_dwordx2 v[30:31], v[40:41], off
	v_pk_mul_f32 v[38:39], v[24:25], v[34:35] op_sel_hi:[1,0]
	v_pk_mul_f32 v[40:41], v[22:23], v[34:35] op_sel_hi:[1,0]
	v_pk_mul_f32 v[38:39], v[12:13], v[38:39]
	v_pk_mul_f32 v[40:41], v[10:11], v[40:41]
	v_pk_fma_f32 v[38:39], v[68:69], v[38:39], v[72:73]
	v_pk_fma_f32 v[40:41], v[66:67], v[40:41], v[70:71]
	s_nop 0
	v_cvt_pk_bf16_f32 v40, v40, v41
	v_cvt_pk_bf16_f32 v41, v38, v39
	v_pk_mul_f32 v[38:39], v[20:21], v[34:35] op_sel_hi:[1,0]
	v_pk_mul_f32 v[34:35], v[18:19], v[34:35] op_sel_hi:[1,0]
	v_pk_mul_f32 v[38:39], v[16:17], v[38:39]
	v_pk_mul_f32 v[34:35], v[14:15], v[34:35]
	v_pk_fma_f32 v[38:39], v[76:77], v[38:39], v[80:81]
	v_pk_fma_f32 v[34:35], v[74:75], v[34:35], v[78:79]
	v_subrev_u32_e32 v30, vcc_lo, v36
	v_add_u32_e32 v30, 0x400, v30
	v_and_b32_e32 v32, 0x7ff, v30
	v_lshrrev_b32_e32 v30, 11, v30
	v_lshlrev_b32_e32 v30, 6, v30
	v_lshrrev_b32_e32 v33, 6, v32
	v_lshl_or_b32 v30, v33, 20, v30
	v_and_or_b32 v30, v32, 63, v30
	v_mov_b32_e32 v31, 0
	v_lshl_add_u64 v[30:31], vcc, 0, v[30:31]
	global_store_dwordx2 v[30:31], v[40:41], off
	v_cvt_pk_bf16_f32 v34, v34, v35
	v_cvt_pk_bf16_f32 v35, v38, v39
	v_subrev_u32_e32 v30, vcc_lo, v36
	v_add_u32_e32 v30, 0x600, v30
	v_and_b32_e32 v32, 0x7ff, v30
	v_lshrrev_b32_e32 v30, 11, v30
	v_lshlrev_b32_e32 v30, 6, v30
	v_lshrrev_b32_e32 v33, 6, v32
	v_lshl_or_b32 v30, v33, 20, v30
	v_and_or_b32 v30, v32, 63, v30
	v_mov_b32_e32 v31, 0
	v_lshl_add_u64 v[30:31], vcc, 0, v[30:31]
	global_store_dwordx2 v[30:31], v[34:35], off
	s_branch .LBB0_317

.LBB0_520:
	s_and_b64 vcc, exec, s[6:7]
	s_cbranch_vccz .LBB0_65
	s_lshl_b32 s6, s71, 2
	s_abs_i32 s7, s6
	v_cvt_f32_u32_e32 v0, s7
	s_sub_i32 s21, 0, s7
	s_add_i32 s20, s6, 0x3fff
	s_xor_b32 s6, s20, s6
	v_rcp_iflag_f32_e32 v0, v0
	s_abs_i32 s20, s20
	s_waitcnt vmcnt(0)
	v_mov_b32_e32 v18, v154
	s_waitcnt vmcnt(3)
	v_mov_b32_e32 v2, v154
	v_mul_f32_e32 v0, 0x4f7ffffe, v0
	v_cvt_u32_f32_e32 v0, v0
	s_ashr_i32 s6, s6, 31
	v_readfirstlane_b32 s26, v0
	s_mul_i32 s21, s21, s26
	s_mul_hi_u32 s21, s26, s21
	s_add_i32 s26, s26, s21
	s_mul_hi_u32 s21, s20, s26
	s_mul_i32 s26, s21, s7
	v_readfirstlane_b32 s18, v2
	s_sub_i32 s20, s20, s26
	s_ashr_i32 s18, s18, 6
	s_add_i32 s26, s21, 1
	s_sub_i32 s27, s20, s7
	s_cmp_ge_u32 s20, s7
	s_cselect_b32 s21, s26, s21
	s_cselect_b32 s20, s27, s20
	s_add_i32 s26, s21, 1
	s_cmp_ge_u32 s20, s7
	s_cselect_b32 s7, s26, s21
	s_xor_b32 s7, s7, s6
	s_sub_i32 s7, s7, s6
	s_lshl_b32 s6, s3, 2
	s_add_i32 s6, s18, s6
	s_mul_i32 s6, s6, s7
	s_cmpk_gt_i32 s6, 0x3fff
	s_cbranch_scc1 .LBB0_65
	s_load_dwordx2 s[20:21], s[0:1], 0x110
	s_waitcnt lgkmcnt(0)
	s_add_u32 s30, s30, 0x1000
	s_addc_u32 s31, s31, 0
	s_ashr_i32 s18, s6, 12
	v_lshlrev_b32_e32 v0, 2, v18
	s_cmp_lg_u64 s[20:21], 0
	s_mul_i32 s20, s18, 0x1800
	s_cselect_b64 s[36:37], -1, 0
	s_ashr_i32 s21, s20, 31
	s_lshl_b64 s[20:21], s[20:21], 2
	s_add_u32 s18, s66, s20
	s_addc_u32 s20, s80, s21
	v_and_b32_e32 v19, 0xfc, v0
	s_add_u32 s34, s18, 0x5000
	s_addc_u32 s35, s20, 0
	s_and_b64 vcc, exec, s[36:37]
	v_lshlrev_b32_e32 v0, 2, v19
	s_cbranch_vccz .LBB0_524
	global_load_dwordx4 v[188:191], v0, s[34:35]
	s_add_u32 s54, s34, 0x30000
	s_addc_u32 s55, s35, 0
	global_load_dwordx4 v[192:195], v0, s[54:55]
	s_add_u32 s56, s34, 0x60000
	s_addc_u32 s57, s35, 0
	global_load_dwordx4 v[196:199], v0, s[56:57]
	s_add_u32 s62, s34, 0x90000
	s_addc_u32 s63, s35, 0
	global_load_dwordx4 v[200:203], v0, s[62:63]
	global_load_dwordx4 v[2:5], v0, s[30:31]
	s_waitcnt vmcnt(0)
	v_pk_add_f32 v[52:53], v[190:191], v[194:195]
	v_pk_add_f32 v[52:53], v[52:53], v[198:199]
	v_pk_add_f32 v[52:53], v[52:53], v[202:203]
	v_pk_add_f32 v[50:51], v[188:189], v[192:193]
	v_pk_add_f32 v[50:51], v[50:51], v[196:197]
	v_pk_add_f32 v[50:51], v[50:51], v[200:201]
.LBB0_524:
	s_waitcnt vmcnt(2)
	v_cndmask_b32_e64 v6, 0, 1, s[36:37]
	v_cmp_ne_u32_e64 s[38:39], 1, v6
	s_andn2_b64 vcc, exec, s[36:37]
	s_cbranch_vccnz .LBB0_526
	global_load_dwordx4 v[188:191], v0, s[34:35] offset:1024
	s_add_u32 s54, s34, 0x30000
	s_addc_u32 s55, s35, 0
	global_load_dwordx4 v[192:195], v0, s[54:55] offset:1024
	s_add_u32 s56, s34, 0x60000
	s_addc_u32 s57, s35, 0
	global_load_dwordx4 v[196:199], v0, s[56:57] offset:1024
	s_add_u32 s62, s34, 0x90000
	s_addc_u32 s63, s35, 0
	global_load_dwordx4 v[200:203], v0, s[62:63] offset:1024
	global_load_dwordx4 v[6:9], v0, s[30:31] offset:1024
	s_waitcnt vmcnt(0)
	v_pk_add_f32 v[54:55], v[188:189], v[192:193]
	v_pk_add_f32 v[54:55], v[54:55], v[196:197]
	v_pk_add_f32 v[54:55], v[54:55], v[200:201]
	v_pk_add_f32 v[56:57], v[190:191], v[194:195]
	v_pk_add_f32 v[56:57], v[56:57], v[198:199]
	v_pk_add_f32 v[56:57], v[56:57], v[202:203]
.LBB0_526:
	s_and_b64 vcc, exec, s[38:39]
	s_cbranch_vccnz .LBB0_528
	global_load_dwordx4 v[188:191], v0, s[34:35] offset:2048
	s_add_u32 s54, s34, 0x30000
	s_addc_u32 s55, s35, 0
	global_load_dwordx4 v[192:195], v0, s[54:55] offset:2048
	s_add_u32 s56, s34, 0x60000
	s_addc_u32 s57, s35, 0
	global_load_dwordx4 v[196:199], v0, s[56:57] offset:2048
	s_add_u32 s62, s34, 0x90000
	s_addc_u32 s63, s35, 0
	global_load_dwordx4 v[200:203], v0, s[62:63] offset:2048
	global_load_dwordx4 v[10:13], v0, s[30:31] offset:2048
	s_waitcnt vmcnt(0)
	v_pk_add_f32 v[58:59], v[188:189], v[192:193]
	v_pk_add_f32 v[58:59], v[58:59], v[196:197]
	v_pk_add_f32 v[58:59], v[58:59], v[200:201]
	v_pk_add_f32 v[60:61], v[190:191], v[194:195]
	v_pk_add_f32 v[60:61], v[60:61], v[198:199]
	v_pk_add_f32 v[60:61], v[60:61], v[202:203]
.LBB0_528:
	s_and_b64 vcc, exec, s[38:39]
	s_cbranch_vccnz .LBB0_530
	global_load_dwordx4 v[188:191], v0, s[34:35] offset:3072
	s_add_u32 s54, s34, 0x30000
	s_addc_u32 s55, s35, 0
	global_load_dwordx4 v[192:195], v0, s[54:55] offset:3072
	s_add_u32 s56, s34, 0x60000
	s_addc_u32 s57, s35, 0
	global_load_dwordx4 v[196:199], v0, s[56:57] offset:3072
	s_add_u32 s62, s34, 0x90000
	s_addc_u32 s63, s35, 0
	global_load_dwordx4 v[200:203], v0, s[62:63] offset:3072
	global_load_dwordx4 v[14:17], v0, s[30:31] offset:3072
	s_waitcnt vmcnt(0)
	v_pk_add_f32 v[62:63], v[188:189], v[192:193]
	v_pk_add_f32 v[62:63], v[62:63], v[196:197]
	v_pk_add_f32 v[62:63], v[62:63], v[200:201]
	v_pk_add_f32 v[64:65], v[190:191], v[194:195]
	v_pk_add_f32 v[64:65], v[64:65], v[198:199]
	v_pk_add_f32 v[64:65], v[64:65], v[202:203]

.LBB0_538:
	s_and_b64 vcc, exec, s[38:39]
	s_cbranch_vccnz .LBB0_540
	s_waitcnt vmcnt(3)
	v_and_b32_e32 v93, 0xffff0000, v88
	s_waitcnt vmcnt(2)
	v_and_b32_e32 v92, 0xffff0000, v86
	v_lshlrev_b32_e32 v91, 16, v88
	v_lshlrev_b32_e32 v90, 16, v86
	v_pk_mul_f32 v[106:107], v[92:93], v[92:93]
	s_waitcnt vmcnt(1)
	v_and_b32_e32 v111, 0xffff0000, v84
	s_waitcnt vmcnt(0)
	v_and_b32_e32 v110, 0xffff0000, v82
	v_lshlrev_b32_e32 v95, 16, v89
	v_lshlrev_b32_e32 v94, 16, v87
	v_pk_fma_f32 v[106:107], v[90:91], v[90:91], v[106:107]
	v_lshlrev_b32_e32 v109, 16, v84
	v_lshlrev_b32_e32 v108, 16, v82
	v_pk_mul_f32 v[116:117], v[110:111], v[110:111]
	v_and_b32_e32 v97, 0xffff0000, v89
	v_and_b32_e32 v96, 0xffff0000, v87
	v_pk_fma_f32 v[106:107], v[94:95], v[94:95], v[106:107]
	v_lshlrev_b32_e32 v113, 16, v85
	v_lshlrev_b32_e32 v112, 16, v83
	v_pk_fma_f32 v[116:117], v[108:109], v[108:109], v[116:117]
	v_pk_fma_f32 v[106:107], v[96:97], v[96:97], v[106:107]
	v_and_b32_e32 v115, 0xffff0000, v85
	v_and_b32_e32 v114, 0xffff0000, v83
	v_pk_fma_f32 v[116:117], v[112:113], v[112:113], v[116:117]
	v_pk_fma_f32 v[116:117], v[114:115], v[114:115], v[116:117]
	v_add_f32_e32 v0, v106, v107
	v_add_f32_e32 v0, v117, v0
	v_add_f32_e32 v0, v116, v0
	s_nop 1
	v_add_f32_dpp v0, v0, v0 row_shr:1 row_mask:0xf bank_mask:0xf
	s_nop 1
	v_add_f32_dpp v0, v0, v0 row_shr:2 row_mask:0xf bank_mask:0xf
	s_nop 1
	v_add_f32_dpp v0, v0, v0 row_shr:4 row_mask:0xf bank_mask:0xf
	s_nop 1
	v_add_f32_dpp v0, v0, v0 row_shr:8 row_mask:0xf bank_mask:0xf
	s_nop 1
	v_readlane_b32 s54, v0, 15
	v_readlane_b32 s55, v0, 31
	v_readlane_b32 s56, v0, 47
	v_readlane_b32 s57, v0, 63
	s_nop 3
	v_mov_b32_e32 v0, s54
	v_add_f32_e32 v0, s55, v0
	v_add_f32_e32 v0, s56, v0
	v_add_f32_e32 v0, s57, v0
	v_mov_b32_e32 v106, v95
	v_mov_b32_e32 v107, v97
	v_mov_b32_e32 v116, v91
	v_mov_b32_e32 v117, v93
	v_mov_b32_e32 v95, v96
	v_mov_b32_e32 v91, v92
	v_fmamk_f32 v0, v0, 0x3a800000, v155
	v_mul_f32_e32 v99, 0x4b800000, v0
	v_cmp_gt_f32_e32 vcc, s84, v0
	s_nop 1
	v_cndmask_b32_e32 v0, v0, v99, vcc
	v_rsq_f32_e32 v0, v0
	s_nop 0
	v_mul_f32_e32 v99, 0x45800000, v0
	v_cndmask_b32_e32 v0, v0, v99, vcc
	v_pk_mul_f32 v[106:107], v[106:107], v[0:1] op_sel_hi:[1,0]
	v_pk_mul_f32 v[116:117], v[116:117], v[0:1] op_sel_hi:[1,0]
	v_pk_mul_f32 v[106:107], v[52:53], v[106:107]
	v_pk_mul_f32 v[116:117], v[50:51], v[116:117]
	v_pk_fma_f32 v[48:49], v[4:5], v[106:107], v[48:49]
	v_pk_fma_f32 v[46:47], v[2:3], v[116:117], v[46:47]
	global_store_dwordx4 v[70:71], v[46:49], off offset:-2048 nt
	s_nop 1
	v_pk_mul_f32 v[46:47], v[94:95], v[0:1] op_sel_hi:[1,0]
	v_pk_mul_f32 v[48:49], v[90:91], v[0:1] op_sel_hi:[1,0]
	v_pk_mul_f32 v[46:47], v[56:57], v[46:47]
	v_pk_mul_f32 v[48:49], v[54:55], v[48:49]
	v_pk_fma_f32 v[44:45], v[8:9], v[46:47], v[44:45]
	v_pk_fma_f32 v[42:43], v[6:7], v[48:49], v[42:43]
	global_store_dwordx4 v[70:71], v[42:45], off offset:-1024 nt
	s_nop 1
	v_mov_b32_e32 v42, v113
	v_mov_b32_e32 v43, v115
	v_mov_b32_e32 v44, v109
	v_mov_b32_e32 v45, v111
	v_pk_mul_f32 v[42:43], v[42:43], v[0:1] op_sel_hi:[1,0]
	v_pk_mul_f32 v[44:45], v[44:45], v[0:1] op_sel_hi:[1,0]
	v_pk_mul_f32 v[42:43], v[60:61], v[42:43]
	v_pk_mul_f32 v[44:45], v[58:59], v[44:45]
	v_pk_fma_f32 v[40:41], v[12:13], v[42:43], v[40:41]
	v_pk_fma_f32 v[38:39], v[10:11], v[44:45], v[38:39]
	v_mov_b32_e32 v113, v114
	v_mov_b32_e32 v109, v110
	global_store_dwordx4 v[70:71], v[38:41], off nt
	s_nop 1
	v_pk_mul_f32 v[38:39], v[112:113], v[0:1] op_sel_hi:[1,0]
	v_pk_mul_f32 v[40:41], v[108:109], v[0:1] op_sel_hi:[1,0]
	v_pk_mul_f32 v[38:39], v[64:65], v[38:39]
	v_pk_mul_f32 v[40:41], v[62:63], v[40:41]
	v_pk_fma_f32 v[36:37], v[16:17], v[38:39], v[36:37]
	v_pk_fma_f32 v[34:35], v[14:15], v[40:41], v[34:35]
	global_store_dwordx4 v[70:71], v[34:37], off offset:1024 nt
.LBB0_540:
	s_andn2_b64 vcc, exec, s[28:29]
	s_cbranch_vccnz .LBB0_532
	s_and_b64 vcc, exec, s[38:39]
	s_cbranch_vccnz .LBB0_532
	s_nop 1
	v_and_b32_e32 v37, 0xffff0000, v80
	v_and_b32_e32 v36, 0xffff0000, v78
	v_lshlrev_b32_e32 v35, 16, v80
	v_lshlrev_b32_e32 v34, 16, v78
	v_pk_mul_f32 v[42:43], v[36:37], v[36:37]
	v_lshlrev_b32_e32 v39, 16, v81
	v_lshlrev_b32_e32 v38, 16, v79
	v_pk_fma_f32 v[42:43], v[34:35], v[34:35], v[42:43]
	v_and_b32_e32 v41, 0xffff0000, v81
	v_and_b32_e32 v40, 0xffff0000, v79
	v_pk_fma_f32 v[42:43], v[38:39], v[38:39], v[42:43]
	v_and_b32_e32 v47, 0xffff0000, v76
	v_and_b32_e32 v46, 0xffff0000, v74
	v_pk_fma_f32 v[42:43], v[40:41], v[40:41], v[42:43]
	v_lshlrev_b32_e32 v45, 16, v76
	v_lshlrev_b32_e32 v44, 16, v74
	v_pk_mul_f32 v[92:93], v[46:47], v[46:47]
	v_lshlrev_b32_e32 v49, 16, v77
	v_lshlrev_b32_e32 v48, 16, v75
	v_pk_fma_f32 v[92:93], v[44:45], v[44:45], v[92:93]
	v_add_f32_e32 v0, v42, v43
	v_and_b32_e32 v91, 0xffff0000, v77
	v_and_b32_e32 v90, 0xffff0000, v75
	v_pk_fma_f32 v[92:93], v[48:49], v[48:49], v[92:93]
	v_pk_fma_f32 v[92:93], v[90:91], v[90:91], v[92:93]
	v_add_f32_e32 v0, v93, v0
	v_add_f32_e32 v0, v92, v0
	s_nop 1
	v_add_f32_dpp v0, v0, v0 row_shr:1 row_mask:0xf bank_mask:0xf
	s_nop 1
	v_add_f32_dpp v0, v0, v0 row_shr:2 row_mask:0xf bank_mask:0xf
	s_nop 1
	v_add_f32_dpp v0, v0, v0 row_shr:4 row_mask:0xf bank_mask:0xf
	s_nop 1
	v_add_f32_dpp v0, v0, v0 row_shr:8 row_mask:0xf bank_mask:0xf
	s_nop 1
	v_readlane_b32 s54, v0, 15
	v_readlane_b32 s55, v0, 31
	v_readlane_b32 s56, v0, 47
	v_readlane_b32 s57, v0, 63
	s_nop 3
	v_mov_b32_e32 v0, s54
	v_add_f32_e32 v0, s55, v0
	v_add_f32_e32 v0, s56, v0
	v_add_f32_e32 v0, s57, v0
	v_mov_b32_e32 v92, v39
	v_mov_b32_e32 v94, v35
	v_mov_b32_e32 v39, v40
	v_mov_b32_e32 v35, v36
	v_mov_b32_e32 v95, v37
	v_mov_b32_e32 v93, v41
	s_ashr_i32 s27, s26, 31
	s_lshl_b64 s[20:21], s[26:27], 12
	v_fmamk_f32 v0, v0, 0x3a800000, v155
	v_mul_f32_e32 v42, 0x4b800000, v0
	v_cmp_gt_f32_e32 vcc, s84, v0
	s_nop 1
	v_cndmask_b32_e32 v0, v0, v42, vcc
	v_rsq_f32_e32 v0, v0
	s_nop 0
	v_mul_f32_e32 v42, 0x45800000, v0
	v_cndmask_b32_e32 v0, v0, v42, vcc
	v_pk_mul_f32 v[38:39], v[38:39], v[0:1] op_sel_hi:[1,0]
	v_pk_mul_f32 v[34:35], v[34:35], v[0:1] op_sel_hi:[1,0]
	v_pk_mul_f32 v[36:37], v[56:57], v[38:39]
	v_pk_mul_f32 v[34:35], v[54:55], v[34:35]
	v_pk_fma_f32 v[28:29], v[8:9], v[36:37], v[28:29]
	v_pk_fma_f32 v[26:27], v[6:7], v[34:35], v[26:27]
	v_mov_b32_e32 v34, v49
	v_mov_b32_e32 v35, v91
	v_mov_b32_e32 v36, v45
	v_mov_b32_e32 v37, v47
	v_pk_mul_f32 v[34:35], v[34:35], v[0:1] op_sel_hi:[1,0]
	v_pk_mul_f32 v[36:37], v[36:37], v[0:1] op_sel_hi:[1,0]
	v_pk_mul_f32 v[34:35], v[60:61], v[34:35]
	v_pk_mul_f32 v[36:37], v[58:59], v[36:37]
	v_mov_b32_e32 v49, v90
	v_mov_b32_e32 v45, v46
	v_pk_mul_f32 v[92:93], v[92:93], v[0:1] op_sel_hi:[1,0]
	v_pk_mul_f32 v[94:95], v[94:95], v[0:1] op_sel_hi:[1,0]
	v_pk_fma_f32 v[24:25], v[12:13], v[34:35], v[24:25]
	v_pk_fma_f32 v[22:23], v[10:11], v[36:37], v[22:23]
	v_pk_mul_f32 v[34:35], v[48:49], v[0:1] op_sel_hi:[1,0]
	v_pk_mul_f32 v[36:37], v[44:45], v[0:1] op_sel_hi:[1,0]
	v_pk_mul_f32 v[94:95], v[50:51], v[94:95]
	v_pk_mul_f32 v[92:93], v[52:53], v[92:93]
	v_pk_mul_f32 v[36:37], v[62:63], v[36:37]
	v_pk_mul_f32 v[34:35], v[64:65], v[34:35]
	v_lshl_add_u64 v[42:43], v[66:67], 0, s[20:21]
	v_pk_fma_f32 v[32:33], v[4:5], v[92:93], v[32:33]
	v_pk_fma_f32 v[30:31], v[2:3], v[94:95], v[30:31]
	v_pk_fma_f32 v[20:21], v[16:17], v[34:35], v[20:21]
	v_pk_fma_f32 v[18:19], v[14:15], v[36:37], v[18:19]
	global_store_dwordx4 v[42:43], v[30:33], off nt
	global_store_dwordx4 v[42:43], v[26:29], off offset:1024 nt
	global_store_dwordx4 v[42:43], v[22:25], off offset:2048 nt
	global_store_dwordx4 v[42:43], v[18:21], off offset:3072 nt
	s_branch .LBB0_532
